# prologue rebalanced: adaLN tables as 192 half-units (one request batch per thread, odd workgroups take their Fourier item first), one Fourier item per workgroup, early transposes on workgroups 192..25
# baseline (speedup 1.0000x reference)
.LBB0_15:
	s_or_b64 exec, exec, s[8:9]
	s_mov_b32 s101, 0
	s_mov_b32 s98, 0
	s_cmp_lg_u32 s74, 0x100
	s_cbranch_scc1 .Lad_skip
	s_cmp_lg_u32 s75, 0
	s_cbranch_scc1 .Lad_skip
	s_mov_b32 s101, 1
	s_cmp_gt_u32 s93, 0xbf
	s_cbranch_scc1 .Lad_skip
	s_bitcmp1_b32 s93, 0
	s_cselect_b32 s98, 1, 0
	s_cbranch_scc1 .Lad_skip
.Lad_body:
	s_load_dwordx2 s[44:45], s[82:83], 0x8
	s_load_dwordx2 s[42:43], s[82:83], 0x18
	s_load_dwordx2 s[40:41], s[82:83], 0x20
	s_load_dwordx2 s[38:39], s[82:83], 0x28
	s_lshr_b32 s22, s93, 1
	s_and_b32 s23, s93, 1
	s_cmp_gt_u32 s22, 47
	s_cselect_b32 s24, 1, 0
	s_mul_i32 s25, s24, 48
	s_sub_u32 s25, s22, s25
	s_lshl_b32 s25, s25, 7
	s_lshl_b32 s23, s23, 6
	s_add_u32 s25, s25, s23
	v_lshlrev_b32_e32 v30, 2, v102
	v_and_b32_e32 v31, 15, v102
	v_lshrrev_b32_e32 v32, 4, v102
	v_mul_u32_u24_e32 v33, 0x6000, v32
	v_lshl_add_u32 v33, v31, 4, v33
	v_lshlrev_b32_e32 v34, 2, v32
	v_mul_u32_u24_e32 v35, 0x50, v32
	v_add_u32_e32 v35, v35, v31
	v_lshlrev_b32_e32 v35, 4, v35
	s_waitcnt lgkmcnt(0)
	global_load_dword v40, v30, s[44:45]
	global_load_dword v41, v30, s[44:45] offset:2048
	s_add_u32 s44, s44, 0x1000
	s_addc_u32 s45, s45, 0
	global_load_dword v42, v30, s[44:45]
	global_load_dword v43, v30, s[44:45] offset:2048
	s_add_u32 s44, s44, 0x1000
	s_addc_u32 s45, s45, 0
	global_load_dword v44, v30, s[44:45]
	global_load_dword v45, v30, s[44:45] offset:2048
	s_add_u32 s44, s44, 0x1000
	s_addc_u32 s45, s45, 0
	global_load_dword v46, v30, s[44:45]
	global_load_dword v47, v30, s[44:45] offset:2048
	global_load_dword v48, v30, s[42:43]
	global_load_dword v49, v30, s[42:43] offset:2048
	s_mul_i32 s26, s24, 0x1800000
	s_lshl_b32 s27, s25, 2
	s_add_u32 s26, s26, s27
	s_add_u32 s46, s40, s26
	s_addc_u32 s47, s41, 0
	global_load_dwordx4 v[126:129], v33, s[46:47]
	s_add_u32 s46, s46, 0xc0000
	s_addc_u32 s47, s47, 0
	global_load_dwordx4 v[130:133], v33, s[46:47]
	s_add_u32 s46, s46, 0xc0000
	s_addc_u32 s47, s47, 0
	global_load_dwordx4 v[134:137], v33, s[46:47]
	s_add_u32 s46, s46, 0xc0000
	s_addc_u32 s47, s47, 0
	global_load_dwordx4 v[138:141], v33, s[46:47]
	s_add_u32 s46, s46, 0xc0000
	s_addc_u32 s47, s47, 0
	global_load_dwordx4 v[142:145], v33, s[46:47]
	s_add_u32 s46, s46, 0xc0000
	s_addc_u32 s47, s47, 0
	global_load_dwordx4 v[146:149], v33, s[46:47]
	s_add_u32 s46, s46, 0xc0000
	s_addc_u32 s47, s47, 0
	global_load_dwordx4 v[150:153], v33, s[46:47]
	s_add_u32 s46, s46, 0xc0000
	s_addc_u32 s47, s47, 0
	global_load_dwordx4 v[154:157], v33, s[46:47]
	s_add_u32 s46, s46, 0xc0000
	s_addc_u32 s47, s47, 0
	global_load_dwordx4 v[158:161], v33, s[46:47]
	s_add_u32 s46, s46, 0xc0000
	s_addc_u32 s47, s47, 0
	global_load_dwordx4 v[162:165], v33, s[46:47]
	s_add_u32 s46, s46, 0xc0000
	s_addc_u32 s47, s47, 0
	global_load_dwordx4 v[166:169], v33, s[46:47]
	s_add_u32 s46, s46, 0xc0000
	s_addc_u32 s47, s47, 0
	global_load_dwordx4 v[170:173], v33, s[46:47]
	s_add_u32 s46, s46, 0xc0000
	s_addc_u32 s47, s47, 0
	global_load_dwordx4 v[174:177], v33, s[46:47]
	s_add_u32 s46, s46, 0xc0000
	s_addc_u32 s47, s47, 0
	global_load_dwordx4 v[178:181], v33, s[46:47]
	s_add_u32 s46, s46, 0xc0000
	s_addc_u32 s47, s47, 0
	global_load_dwordx4 v[182:185], v33, s[46:47]
	s_add_u32 s46, s46, 0xc0000
	s_addc_u32 s47, s47, 0
	global_load_dwordx4 v[186:189], v33, s[46:47]
	s_add_u32 s46, s46, 0xc0000
	s_addc_u32 s47, s47, 0
	global_load_dwordx4 v[190:193], v33, s[46:47]
	s_add_u32 s46, s46, 0xc0000
	s_addc_u32 s47, s47, 0
	global_load_dwordx4 v[194:197], v33, s[46:47]
	s_add_u32 s46, s46, 0xc0000
	s_addc_u32 s47, s47, 0
	global_load_dwordx4 v[198:201], v33, s[46:47]
	s_add_u32 s46, s46, 0xc0000
	s_addc_u32 s47, s47, 0
	global_load_dwordx4 v[202:205], v33, s[46:47]
	s_add_u32 s46, s46, 0xc0000
	s_addc_u32 s47, s47, 0
	global_load_dwordx4 v[206:209], v33, s[46:47]
	s_add_u32 s46, s46, 0xc0000
	s_addc_u32 s47, s47, 0
	global_load_dwordx4 v[210:213], v33, s[46:47]
	s_add_u32 s46, s46, 0xc0000
	s_addc_u32 s47, s47, 0
	global_load_dwordx4 v[214:217], v33, s[46:47]
	s_add_u32 s46, s46, 0xc0000
	s_addc_u32 s47, s47, 0
	global_load_dwordx4 v[218:221], v33, s[46:47]
	s_add_u32 s46, s46, 0xc0000
	s_addc_u32 s47, s47, 0
	global_load_dwordx4 v[222:225], v33, s[46:47]
	s_add_u32 s46, s46, 0xc0000
	s_addc_u32 s47, s47, 0
	global_load_dwordx4 v[226:229], v33, s[46:47]
	s_add_u32 s46, s46, 0xc0000
	s_addc_u32 s47, s47, 0
	global_load_dwordx4 v[230:233], v33, s[46:47]
	s_add_u32 s46, s46, 0xc0000
	s_addc_u32 s47, s47, 0
	global_load_dwordx4 v[234:237], v33, s[46:47]
	s_add_u32 s46, s46, 0xc0000
	s_addc_u32 s47, s47, 0
	global_load_dwordx4 v[238:241], v33, s[46:47]
	s_add_u32 s46, s46, 0xc0000
	s_addc_u32 s47, s47, 0
	global_load_dwordx4 v[242:245], v33, s[46:47]
	s_add_u32 s46, s46, 0xc0000
	s_addc_u32 s47, s47, 0
	global_load_dwordx4 v[246:249], v33, s[46:47]
	s_add_u32 s46, s46, 0xc0000
	s_addc_u32 s47, s47, 0
	global_load_dwordx4 v[250:253], v33, s[46:47]
	s_add_u32 s46, s46, 0xc0000
	s_addc_u32 s47, s47, 0
	s_waitcnt vmcnt(41)
	v_mul_f32_e32 v50, 0xbfb8aa3b, v40
	v_exp_f32_e32 v50, v50
	s_nop 0
	v_add_f32_e32 v50, 1.0, v50
	v_rcp_f32_e32 v50, v50
	s_nop 0
	v_mul_f32_e32 v50, v40, v50
	ds_write_b32 v30, v50
	s_waitcnt vmcnt(40)
	v_mul_f32_e32 v50, 0xbfb8aa3b, v41
	v_exp_f32_e32 v50, v50
	s_nop 0
	v_add_f32_e32 v50, 1.0, v50
	v_rcp_f32_e32 v50, v50
	s_nop 0
	v_mul_f32_e32 v50, v41, v50
	ds_write_b32 v30, v50 offset:2048
	s_waitcnt vmcnt(39)
	v_mul_f32_e32 v50, 0xbfb8aa3b, v42
	v_exp_f32_e32 v50, v50
	s_nop 0
	v_add_f32_e32 v50, 1.0, v50
	v_rcp_f32_e32 v50, v50
	s_nop 0
	v_mul_f32_e32 v50, v42, v50
	ds_write_b32 v30, v50 offset:4096
	s_waitcnt vmcnt(38)
	v_mul_f32_e32 v50, 0xbfb8aa3b, v43
	v_exp_f32_e32 v50, v50
	s_nop 0
	v_add_f32_e32 v50, 1.0, v50
	v_rcp_f32_e32 v50, v50
	s_nop 0
	v_mul_f32_e32 v50, v43, v50
	ds_write_b32 v30, v50 offset:6144
	s_waitcnt vmcnt(37)
	v_mul_f32_e32 v50, 0xbfb8aa3b, v44
	v_exp_f32_e32 v50, v50
	s_nop 0
	v_add_f32_e32 v50, 1.0, v50
	v_rcp_f32_e32 v50, v50
	s_nop 0
	v_mul_f32_e32 v50, v44, v50
	ds_write_b32 v30, v50 offset:8192
	s_waitcnt vmcnt(36)
	v_mul_f32_e32 v50, 0xbfb8aa3b, v45
	v_exp_f32_e32 v50, v50
	s_nop 0
	v_add_f32_e32 v50, 1.0, v50
	v_rcp_f32_e32 v50, v50
	s_nop 0
	v_mul_f32_e32 v50, v45, v50
	ds_write_b32 v30, v50 offset:10240
	s_waitcnt vmcnt(35)
	v_mul_f32_e32 v50, 0xbfb8aa3b, v46
	v_exp_f32_e32 v50, v50
	s_nop 0
	v_add_f32_e32 v50, 1.0, v50
	v_rcp_f32_e32 v50, v50
	s_nop 0
	v_mul_f32_e32 v50, v46, v50
	ds_write_b32 v30, v50 offset:12288
	s_waitcnt vmcnt(34)
	v_mul_f32_e32 v50, 0xbfb8aa3b, v47
	v_exp_f32_e32 v50, v50
	s_nop 0
	v_add_f32_e32 v50, 1.0, v50
	v_rcp_f32_e32 v50, v50
	s_nop 0
	v_mul_f32_e32 v50, v47, v50
	ds_write_b32 v30, v50 offset:14336
	s_waitcnt vmcnt(33)
	v_mul_f32_e32 v50, 0xbfb8aa3b, v48
	v_exp_f32_e32 v50, v50
	s_nop 0
	v_add_f32_e32 v50, 1.0, v50
	v_rcp_f32_e32 v50, v50
	s_nop 0
	v_mul_f32_e32 v50, v48, v50
	ds_write_b32 v30, v50 offset:16384
	s_waitcnt vmcnt(32)
	v_mul_f32_e32 v50, 0xbfb8aa3b, v49
	v_exp_f32_e32 v50, v50
	s_nop 0
	v_add_f32_e32 v50, 1.0, v50
	v_rcp_f32_e32 v50, v50
	s_nop 0
	v_mul_f32_e32 v50, v49, v50
	ds_write_b32 v30, v50 offset:18432
	s_waitcnt lgkmcnt(0)
	s_barrier
	v_mov_b32_e32 v10, 0
	v_mov_b32_e32 v11, 0
	v_mov_b32_e32 v12, 0
	v_mov_b32_e32 v13, 0
	v_mov_b32_e32 v14, 0
	v_mov_b32_e32 v15, 0
	v_mov_b32_e32 v16, 0
	v_mov_b32_e32 v17, 0
	v_mov_b32_e32 v18, 0
	v_mov_b32_e32 v19, 0
	v_mov_b32_e32 v20, 0
	v_mov_b32_e32 v21, 0
	v_mov_b32_e32 v22, 0
	v_mov_b32_e32 v23, 0
	v_mov_b32_e32 v24, 0
	v_mov_b32_e32 v25, 0
	v_mov_b32_e32 v26, 0
	v_mov_b32_e32 v27, 0
	v_mov_b32_e32 v28, 0
	v_mov_b32_e32 v29, 0
	ds_read_b32 v52, v34 offset:0
	ds_read_b32 v53, v34 offset:4096
	ds_read_b32 v54, v34 offset:8192
	ds_read_b32 v55, v34 offset:12288
	ds_read_b32 v56, v34 offset:16384
	ds_read_b32 v57, v34 offset:128
	ds_read_b32 v58, v34 offset:4224
	ds_read_b32 v59, v34 offset:8320
	ds_read_b32 v60, v34 offset:12416
	ds_read_b32 v61, v34 offset:16512
	ds_read_b32 v62, v34 offset:256
	ds_read_b32 v63, v34 offset:4352
	ds_read_b32 v64, v34 offset:8448
	ds_read_b32 v65, v34 offset:12544
	ds_read_b32 v66, v34 offset:16640
	ds_read_b32 v67, v34 offset:384
	ds_read_b32 v68, v34 offset:4480
	ds_read_b32 v69, v34 offset:8576
	ds_read_b32 v70, v34 offset:12672
	ds_read_b32 v71, v34 offset:16768
	s_waitcnt lgkmcnt(0)
	s_waitcnt vmcnt(31)
	v_pk_fma_f32 v[10:11], v[126:127], v[52:53], v[10:11] op_sel_hi:[1,0,1]
	v_pk_fma_f32 v[12:13], v[128:129], v[52:53], v[12:13] op_sel_hi:[1,0,1]
	v_pk_fma_f32 v[14:15], v[126:127], v[52:53], v[14:15] op_sel:[0,1,0]
	v_pk_fma_f32 v[16:17], v[128:129], v[52:53], v[16:17] op_sel:[0,1,0]
	v_pk_fma_f32 v[18:19], v[126:127], v[54:55], v[18:19] op_sel_hi:[1,0,1]
	v_pk_fma_f32 v[20:21], v[128:129], v[54:55], v[20:21] op_sel_hi:[1,0,1]
	v_pk_fma_f32 v[22:23], v[126:127], v[54:55], v[22:23] op_sel:[0,1,0]
	v_pk_fma_f32 v[24:25], v[128:129], v[54:55], v[24:25] op_sel:[0,1,0]
	v_pk_fma_f32 v[26:27], v[126:127], v[56:57], v[26:27] op_sel_hi:[1,0,1]
	v_pk_fma_f32 v[28:29], v[128:129], v[56:57], v[28:29] op_sel_hi:[1,0,1]
	s_waitcnt vmcnt(30)
	v_pk_fma_f32 v[10:11], v[130:131], v[56:57], v[10:11] op_sel:[0,1,0]
	v_pk_fma_f32 v[12:13], v[132:133], v[56:57], v[12:13] op_sel:[0,1,0]
	v_pk_fma_f32 v[14:15], v[130:131], v[58:59], v[14:15] op_sel_hi:[1,0,1]
	v_pk_fma_f32 v[16:17], v[132:133], v[58:59], v[16:17] op_sel_hi:[1,0,1]
	v_pk_fma_f32 v[18:19], v[130:131], v[58:59], v[18:19] op_sel:[0,1,0]
	v_pk_fma_f32 v[20:21], v[132:133], v[58:59], v[20:21] op_sel:[0,1,0]
	v_pk_fma_f32 v[22:23], v[130:131], v[60:61], v[22:23] op_sel_hi:[1,0,1]
	v_pk_fma_f32 v[24:25], v[132:133], v[60:61], v[24:25] op_sel_hi:[1,0,1]
	v_pk_fma_f32 v[26:27], v[130:131], v[60:61], v[26:27] op_sel:[0,1,0]
	v_pk_fma_f32 v[28:29], v[132:133], v[60:61], v[28:29] op_sel:[0,1,0]
	s_waitcnt vmcnt(29)
	v_pk_fma_f32 v[10:11], v[134:135], v[62:63], v[10:11] op_sel_hi:[1,0,1]
	v_pk_fma_f32 v[12:13], v[136:137], v[62:63], v[12:13] op_sel_hi:[1,0,1]
	v_pk_fma_f32 v[14:15], v[134:135], v[62:63], v[14:15] op_sel:[0,1,0]
	v_pk_fma_f32 v[16:17], v[136:137], v[62:63], v[16:17] op_sel:[0,1,0]
	v_pk_fma_f32 v[18:19], v[134:135], v[64:65], v[18:19] op_sel_hi:[1,0,1]
	v_pk_fma_f32 v[20:21], v[136:137], v[64:65], v[20:21] op_sel_hi:[1,0,1]
	v_pk_fma_f32 v[22:23], v[134:135], v[64:65], v[22:23] op_sel:[0,1,0]
	v_pk_fma_f32 v[24:25], v[136:137], v[64:65], v[24:25] op_sel:[0,1,0]
	v_pk_fma_f32 v[26:27], v[134:135], v[66:67], v[26:27] op_sel_hi:[1,0,1]
	v_pk_fma_f32 v[28:29], v[136:137], v[66:67], v[28:29] op_sel_hi:[1,0,1]
	s_waitcnt vmcnt(28)
	v_pk_fma_f32 v[10:11], v[138:139], v[66:67], v[10:11] op_sel:[0,1,0]
	v_pk_fma_f32 v[12:13], v[140:141], v[66:67], v[12:13] op_sel:[0,1,0]
	v_pk_fma_f32 v[14:15], v[138:139], v[68:69], v[14:15] op_sel_hi:[1,0,1]
	v_pk_fma_f32 v[16:17], v[140:141], v[68:69], v[16:17] op_sel_hi:[1,0,1]
	v_pk_fma_f32 v[18:19], v[138:139], v[68:69], v[18:19] op_sel:[0,1,0]
	v_pk_fma_f32 v[20:21], v[140:141], v[68:69], v[20:21] op_sel:[0,1,0]
	v_pk_fma_f32 v[22:23], v[138:139], v[70:71], v[22:23] op_sel_hi:[1,0,1]
	v_pk_fma_f32 v[24:25], v[140:141], v[70:71], v[24:25] op_sel_hi:[1,0,1]
	v_pk_fma_f32 v[26:27], v[138:139], v[70:71], v[26:27] op_sel:[0,1,0]
	v_pk_fma_f32 v[28:29], v[140:141], v[70:71], v[28:29] op_sel:[0,1,0]
	ds_read_b32 v52, v34 offset:512
	ds_read_b32 v53, v34 offset:4608
	ds_read_b32 v54, v34 offset:8704
	ds_read_b32 v55, v34 offset:12800
	ds_read_b32 v56, v34 offset:16896
	ds_read_b32 v57, v34 offset:640
	ds_read_b32 v58, v34 offset:4736
	ds_read_b32 v59, v34 offset:8832
	ds_read_b32 v60, v34 offset:12928
	ds_read_b32 v61, v34 offset:17024
	ds_read_b32 v62, v34 offset:768
	ds_read_b32 v63, v34 offset:4864
	ds_read_b32 v64, v34 offset:8960
	ds_read_b32 v65, v34 offset:13056
	ds_read_b32 v66, v34 offset:17152
	ds_read_b32 v67, v34 offset:896
	ds_read_b32 v68, v34 offset:4992
	ds_read_b32 v69, v34 offset:9088
	ds_read_b32 v70, v34 offset:13184
	ds_read_b32 v71, v34 offset:17280
	s_waitcnt lgkmcnt(0)
	s_waitcnt vmcnt(27)
	v_pk_fma_f32 v[10:11], v[142:143], v[52:53], v[10:11] op_sel_hi:[1,0,1]
	v_pk_fma_f32 v[12:13], v[144:145], v[52:53], v[12:13] op_sel_hi:[1,0,1]
	v_pk_fma_f32 v[14:15], v[142:143], v[52:53], v[14:15] op_sel:[0,1,0]
	v_pk_fma_f32 v[16:17], v[144:145], v[52:53], v[16:17] op_sel:[0,1,0]
	v_pk_fma_f32 v[18:19], v[142:143], v[54:55], v[18:19] op_sel_hi:[1,0,1]
	v_pk_fma_f32 v[20:21], v[144:145], v[54:55], v[20:21] op_sel_hi:[1,0,1]
	v_pk_fma_f32 v[22:23], v[142:143], v[54:55], v[22:23] op_sel:[0,1,0]
	v_pk_fma_f32 v[24:25], v[144:145], v[54:55], v[24:25] op_sel:[0,1,0]
	v_pk_fma_f32 v[26:27], v[142:143], v[56:57], v[26:27] op_sel_hi:[1,0,1]
	v_pk_fma_f32 v[28:29], v[144:145], v[56:57], v[28:29] op_sel_hi:[1,0,1]
	s_waitcnt vmcnt(26)
	v_pk_fma_f32 v[10:11], v[146:147], v[56:57], v[10:11] op_sel:[0,1,0]
	v_pk_fma_f32 v[12:13], v[148:149], v[56:57], v[12:13] op_sel:[0,1,0]
	v_pk_fma_f32 v[14:15], v[146:147], v[58:59], v[14:15] op_sel_hi:[1,0,1]
	v_pk_fma_f32 v[16:17], v[148:149], v[58:59], v[16:17] op_sel_hi:[1,0,1]
	v_pk_fma_f32 v[18:19], v[146:147], v[58:59], v[18:19] op_sel:[0,1,0]
	v_pk_fma_f32 v[20:21], v[148:149], v[58:59], v[20:21] op_sel:[0,1,0]
	v_pk_fma_f32 v[22:23], v[146:147], v[60:61], v[22:23] op_sel_hi:[1,0,1]
	v_pk_fma_f32 v[24:25], v[148:149], v[60:61], v[24:25] op_sel_hi:[1,0,1]
	v_pk_fma_f32 v[26:27], v[146:147], v[60:61], v[26:27] op_sel:[0,1,0]
	v_pk_fma_f32 v[28:29], v[148:149], v[60:61], v[28:29] op_sel:[0,1,0]
	s_waitcnt vmcnt(25)
	v_pk_fma_f32 v[10:11], v[150:151], v[62:63], v[10:11] op_sel_hi:[1,0,1]
	v_pk_fma_f32 v[12:13], v[152:153], v[62:63], v[12:13] op_sel_hi:[1,0,1]
	v_pk_fma_f32 v[14:15], v[150:151], v[62:63], v[14:15] op_sel:[0,1,0]
	v_pk_fma_f32 v[16:17], v[152:153], v[62:63], v[16:17] op_sel:[0,1,0]
	v_pk_fma_f32 v[18:19], v[150:151], v[64:65], v[18:19] op_sel_hi:[1,0,1]
	v_pk_fma_f32 v[20:21], v[152:153], v[64:65], v[20:21] op_sel_hi:[1,0,1]
	v_pk_fma_f32 v[22:23], v[150:151], v[64:65], v[22:23] op_sel:[0,1,0]
	v_pk_fma_f32 v[24:25], v[152:153], v[64:65], v[24:25] op_sel:[0,1,0]
	v_pk_fma_f32 v[26:27], v[150:151], v[66:67], v[26:27] op_sel_hi:[1,0,1]
	v_pk_fma_f32 v[28:29], v[152:153], v[66:67], v[28:29] op_sel_hi:[1,0,1]
	s_waitcnt vmcnt(24)
	v_pk_fma_f32 v[10:11], v[154:155], v[66:67], v[10:11] op_sel:[0,1,0]
	v_pk_fma_f32 v[12:13], v[156:157], v[66:67], v[12:13] op_sel:[0,1,0]
	v_pk_fma_f32 v[14:15], v[154:155], v[68:69], v[14:15] op_sel_hi:[1,0,1]
	v_pk_fma_f32 v[16:17], v[156:157], v[68:69], v[16:17] op_sel_hi:[1,0,1]
	v_pk_fma_f32 v[18:19], v[154:155], v[68:69], v[18:19] op_sel:[0,1,0]
	v_pk_fma_f32 v[20:21], v[156:157], v[68:69], v[20:21] op_sel:[0,1,0]
	v_pk_fma_f32 v[22:23], v[154:155], v[70:71], v[22:23] op_sel_hi:[1,0,1]
	v_pk_fma_f32 v[24:25], v[156:157], v[70:71], v[24:25] op_sel_hi:[1,0,1]
	v_pk_fma_f32 v[26:27], v[154:155], v[70:71], v[26:27] op_sel:[0,1,0]
	v_pk_fma_f32 v[28:29], v[156:157], v[70:71], v[28:29] op_sel:[0,1,0]
	ds_read_b32 v52, v34 offset:1024
	ds_read_b32 v53, v34 offset:5120
	ds_read_b32 v54, v34 offset:9216
	ds_read_b32 v55, v34 offset:13312
	ds_read_b32 v56, v34 offset:17408
	ds_read_b32 v57, v34 offset:1152
	ds_read_b32 v58, v34 offset:5248
	ds_read_b32 v59, v34 offset:9344
	ds_read_b32 v60, v34 offset:13440
	ds_read_b32 v61, v34 offset:17536
	ds_read_b32 v62, v34 offset:1280
	ds_read_b32 v63, v34 offset:5376
	ds_read_b32 v64, v34 offset:9472
	ds_read_b32 v65, v34 offset:13568
	ds_read_b32 v66, v34 offset:17664
	ds_read_b32 v67, v34 offset:1408
	ds_read_b32 v68, v34 offset:5504
	ds_read_b32 v69, v34 offset:9600
	ds_read_b32 v70, v34 offset:13696
	ds_read_b32 v71, v34 offset:17792
	s_waitcnt lgkmcnt(0)
	s_waitcnt vmcnt(23)
	v_pk_fma_f32 v[10:11], v[158:159], v[52:53], v[10:11] op_sel_hi:[1,0,1]
	v_pk_fma_f32 v[12:13], v[160:161], v[52:53], v[12:13] op_sel_hi:[1,0,1]
	v_pk_fma_f32 v[14:15], v[158:159], v[52:53], v[14:15] op_sel:[0,1,0]
	v_pk_fma_f32 v[16:17], v[160:161], v[52:53], v[16:17] op_sel:[0,1,0]
	v_pk_fma_f32 v[18:19], v[158:159], v[54:55], v[18:19] op_sel_hi:[1,0,1]
	v_pk_fma_f32 v[20:21], v[160:161], v[54:55], v[20:21] op_sel_hi:[1,0,1]
	v_pk_fma_f32 v[22:23], v[158:159], v[54:55], v[22:23] op_sel:[0,1,0]
	v_pk_fma_f32 v[24:25], v[160:161], v[54:55], v[24:25] op_sel:[0,1,0]
	v_pk_fma_f32 v[26:27], v[158:159], v[56:57], v[26:27] op_sel_hi:[1,0,1]
	v_pk_fma_f32 v[28:29], v[160:161], v[56:57], v[28:29] op_sel_hi:[1,0,1]
	s_waitcnt vmcnt(22)
	v_pk_fma_f32 v[10:11], v[162:163], v[56:57], v[10:11] op_sel:[0,1,0]
	v_pk_fma_f32 v[12:13], v[164:165], v[56:57], v[12:13] op_sel:[0,1,0]
	v_pk_fma_f32 v[14:15], v[162:163], v[58:59], v[14:15] op_sel_hi:[1,0,1]
	v_pk_fma_f32 v[16:17], v[164:165], v[58:59], v[16:17] op_sel_hi:[1,0,1]
	v_pk_fma_f32 v[18:19], v[162:163], v[58:59], v[18:19] op_sel:[0,1,0]
	v_pk_fma_f32 v[20:21], v[164:165], v[58:59], v[20:21] op_sel:[0,1,0]
	v_pk_fma_f32 v[22:23], v[162:163], v[60:61], v[22:23] op_sel_hi:[1,0,1]
	v_pk_fma_f32 v[24:25], v[164:165], v[60:61], v[24:25] op_sel_hi:[1,0,1]
	v_pk_fma_f32 v[26:27], v[162:163], v[60:61], v[26:27] op_sel:[0,1,0]
	v_pk_fma_f32 v[28:29], v[164:165], v[60:61], v[28:29] op_sel:[0,1,0]
	s_waitcnt vmcnt(21)
	v_pk_fma_f32 v[10:11], v[166:167], v[62:63], v[10:11] op_sel_hi:[1,0,1]
	v_pk_fma_f32 v[12:13], v[168:169], v[62:63], v[12:13] op_sel_hi:[1,0,1]
	v_pk_fma_f32 v[14:15], v[166:167], v[62:63], v[14:15] op_sel:[0,1,0]
	v_pk_fma_f32 v[16:17], v[168:169], v[62:63], v[16:17] op_sel:[0,1,0]
	v_pk_fma_f32 v[18:19], v[166:167], v[64:65], v[18:19] op_sel_hi:[1,0,1]
	v_pk_fma_f32 v[20:21], v[168:169], v[64:65], v[20:21] op_sel_hi:[1,0,1]
	v_pk_fma_f32 v[22:23], v[166:167], v[64:65], v[22:23] op_sel:[0,1,0]
	v_pk_fma_f32 v[24:25], v[168:169], v[64:65], v[24:25] op_sel:[0,1,0]
	v_pk_fma_f32 v[26:27], v[166:167], v[66:67], v[26:27] op_sel_hi:[1,0,1]
	v_pk_fma_f32 v[28:29], v[168:169], v[66:67], v[28:29] op_sel_hi:[1,0,1]
	s_waitcnt vmcnt(20)
	v_pk_fma_f32 v[10:11], v[170:171], v[66:67], v[10:11] op_sel:[0,1,0]
	v_pk_fma_f32 v[12:13], v[172:173], v[66:67], v[12:13] op_sel:[0,1,0]
	v_pk_fma_f32 v[14:15], v[170:171], v[68:69], v[14:15] op_sel_hi:[1,0,1]
	v_pk_fma_f32 v[16:17], v[172:173], v[68:69], v[16:17] op_sel_hi:[1,0,1]
	v_pk_fma_f32 v[18:19], v[170:171], v[68:69], v[18:19] op_sel:[0,1,0]
	v_pk_fma_f32 v[20:21], v[172:173], v[68:69], v[20:21] op_sel:[0,1,0]
	v_pk_fma_f32 v[22:23], v[170:171], v[70:71], v[22:23] op_sel_hi:[1,0,1]
	v_pk_fma_f32 v[24:25], v[172:173], v[70:71], v[24:25] op_sel_hi:[1,0,1]
	v_pk_fma_f32 v[26:27], v[170:171], v[70:71], v[26:27] op_sel:[0,1,0]
	v_pk_fma_f32 v[28:29], v[172:173], v[70:71], v[28:29] op_sel:[0,1,0]
	ds_read_b32 v52, v34 offset:1536
	ds_read_b32 v53, v34 offset:5632
	ds_read_b32 v54, v34 offset:9728
	ds_read_b32 v55, v34 offset:13824
	ds_read_b32 v56, v34 offset:17920
	ds_read_b32 v57, v34 offset:1664
	ds_read_b32 v58, v34 offset:5760
	ds_read_b32 v59, v34 offset:9856
	ds_read_b32 v60, v34 offset:13952
	ds_read_b32 v61, v34 offset:18048
	ds_read_b32 v62, v34 offset:1792
	ds_read_b32 v63, v34 offset:5888
	ds_read_b32 v64, v34 offset:9984
	ds_read_b32 v65, v34 offset:14080
	ds_read_b32 v66, v34 offset:18176
	ds_read_b32 v67, v34 offset:1920
	ds_read_b32 v68, v34 offset:6016
	ds_read_b32 v69, v34 offset:10112
	ds_read_b32 v70, v34 offset:14208
	ds_read_b32 v71, v34 offset:18304
	s_waitcnt lgkmcnt(0)
	s_waitcnt vmcnt(19)
	v_pk_fma_f32 v[10:11], v[174:175], v[52:53], v[10:11] op_sel_hi:[1,0,1]
	v_pk_fma_f32 v[12:13], v[176:177], v[52:53], v[12:13] op_sel_hi:[1,0,1]
	v_pk_fma_f32 v[14:15], v[174:175], v[52:53], v[14:15] op_sel:[0,1,0]
	v_pk_fma_f32 v[16:17], v[176:177], v[52:53], v[16:17] op_sel:[0,1,0]
	v_pk_fma_f32 v[18:19], v[174:175], v[54:55], v[18:19] op_sel_hi:[1,0,1]
	v_pk_fma_f32 v[20:21], v[176:177], v[54:55], v[20:21] op_sel_hi:[1,0,1]
	v_pk_fma_f32 v[22:23], v[174:175], v[54:55], v[22:23] op_sel:[0,1,0]
	v_pk_fma_f32 v[24:25], v[176:177], v[54:55], v[24:25] op_sel:[0,1,0]
	v_pk_fma_f32 v[26:27], v[174:175], v[56:57], v[26:27] op_sel_hi:[1,0,1]
	v_pk_fma_f32 v[28:29], v[176:177], v[56:57], v[28:29] op_sel_hi:[1,0,1]
	s_waitcnt vmcnt(18)
	v_pk_fma_f32 v[10:11], v[178:179], v[56:57], v[10:11] op_sel:[0,1,0]
	v_pk_fma_f32 v[12:13], v[180:181], v[56:57], v[12:13] op_sel:[0,1,0]
	v_pk_fma_f32 v[14:15], v[178:179], v[58:59], v[14:15] op_sel_hi:[1,0,1]
	v_pk_fma_f32 v[16:17], v[180:181], v[58:59], v[16:17] op_sel_hi:[1,0,1]
	v_pk_fma_f32 v[18:19], v[178:179], v[58:59], v[18:19] op_sel:[0,1,0]
	v_pk_fma_f32 v[20:21], v[180:181], v[58:59], v[20:21] op_sel:[0,1,0]
	v_pk_fma_f32 v[22:23], v[178:179], v[60:61], v[22:23] op_sel_hi:[1,0,1]
	v_pk_fma_f32 v[24:25], v[180:181], v[60:61], v[24:25] op_sel_hi:[1,0,1]
	v_pk_fma_f32 v[26:27], v[178:179], v[60:61], v[26:27] op_sel:[0,1,0]
	v_pk_fma_f32 v[28:29], v[180:181], v[60:61], v[28:29] op_sel:[0,1,0]
	s_waitcnt vmcnt(17)
	v_pk_fma_f32 v[10:11], v[182:183], v[62:63], v[10:11] op_sel_hi:[1,0,1]
	v_pk_fma_f32 v[12:13], v[184:185], v[62:63], v[12:13] op_sel_hi:[1,0,1]
	v_pk_fma_f32 v[14:15], v[182:183], v[62:63], v[14:15] op_sel:[0,1,0]
	v_pk_fma_f32 v[16:17], v[184:185], v[62:63], v[16:17] op_sel:[0,1,0]
	v_pk_fma_f32 v[18:19], v[182:183], v[64:65], v[18:19] op_sel_hi:[1,0,1]
	v_pk_fma_f32 v[20:21], v[184:185], v[64:65], v[20:21] op_sel_hi:[1,0,1]
	v_pk_fma_f32 v[22:23], v[182:183], v[64:65], v[22:23] op_sel:[0,1,0]
	v_pk_fma_f32 v[24:25], v[184:185], v[64:65], v[24:25] op_sel:[0,1,0]
	v_pk_fma_f32 v[26:27], v[182:183], v[66:67], v[26:27] op_sel_hi:[1,0,1]
	v_pk_fma_f32 v[28:29], v[184:185], v[66:67], v[28:29] op_sel_hi:[1,0,1]
	s_waitcnt vmcnt(16)
	v_pk_fma_f32 v[10:11], v[186:187], v[66:67], v[10:11] op_sel:[0,1,0]
	v_pk_fma_f32 v[12:13], v[188:189], v[66:67], v[12:13] op_sel:[0,1,0]
	v_pk_fma_f32 v[14:15], v[186:187], v[68:69], v[14:15] op_sel_hi:[1,0,1]
	v_pk_fma_f32 v[16:17], v[188:189], v[68:69], v[16:17] op_sel_hi:[1,0,1]
	v_pk_fma_f32 v[18:19], v[186:187], v[68:69], v[18:19] op_sel:[0,1,0]
	v_pk_fma_f32 v[20:21], v[188:189], v[68:69], v[20:21] op_sel:[0,1,0]
	v_pk_fma_f32 v[22:23], v[186:187], v[70:71], v[22:23] op_sel_hi:[1,0,1]
	v_pk_fma_f32 v[24:25], v[188:189], v[70:71], v[24:25] op_sel_hi:[1,0,1]
	v_pk_fma_f32 v[26:27], v[186:187], v[70:71], v[26:27] op_sel:[0,1,0]
	v_pk_fma_f32 v[28:29], v[188:189], v[70:71], v[28:29] op_sel:[0,1,0]
	ds_read_b32 v52, v34 offset:2048
	ds_read_b32 v53, v34 offset:6144
	ds_read_b32 v54, v34 offset:10240
	ds_read_b32 v55, v34 offset:14336
	ds_read_b32 v56, v34 offset:18432
	ds_read_b32 v57, v34 offset:2176
	ds_read_b32 v58, v34 offset:6272
	ds_read_b32 v59, v34 offset:10368
	ds_read_b32 v60, v34 offset:14464
	ds_read_b32 v61, v34 offset:18560
	ds_read_b32 v62, v34 offset:2304
	ds_read_b32 v63, v34 offset:6400
	ds_read_b32 v64, v34 offset:10496
	ds_read_b32 v65, v34 offset:14592
	ds_read_b32 v66, v34 offset:18688
	ds_read_b32 v67, v34 offset:2432
	ds_read_b32 v68, v34 offset:6528
	ds_read_b32 v69, v34 offset:10624
	ds_read_b32 v70, v34 offset:14720
	ds_read_b32 v71, v34 offset:18816
	s_waitcnt lgkmcnt(0)
	s_waitcnt vmcnt(15)
	v_pk_fma_f32 v[10:11], v[190:191], v[52:53], v[10:11] op_sel_hi:[1,0,1]
	v_pk_fma_f32 v[12:13], v[192:193], v[52:53], v[12:13] op_sel_hi:[1,0,1]
	v_pk_fma_f32 v[14:15], v[190:191], v[52:53], v[14:15] op_sel:[0,1,0]
	v_pk_fma_f32 v[16:17], v[192:193], v[52:53], v[16:17] op_sel:[0,1,0]
	v_pk_fma_f32 v[18:19], v[190:191], v[54:55], v[18:19] op_sel_hi:[1,0,1]
	v_pk_fma_f32 v[20:21], v[192:193], v[54:55], v[20:21] op_sel_hi:[1,0,1]
	v_pk_fma_f32 v[22:23], v[190:191], v[54:55], v[22:23] op_sel:[0,1,0]
	v_pk_fma_f32 v[24:25], v[192:193], v[54:55], v[24:25] op_sel:[0,1,0]
	v_pk_fma_f32 v[26:27], v[190:191], v[56:57], v[26:27] op_sel_hi:[1,0,1]
	v_pk_fma_f32 v[28:29], v[192:193], v[56:57], v[28:29] op_sel_hi:[1,0,1]
	s_waitcnt vmcnt(14)
	v_pk_fma_f32 v[10:11], v[194:195], v[56:57], v[10:11] op_sel:[0,1,0]
	v_pk_fma_f32 v[12:13], v[196:197], v[56:57], v[12:13] op_sel:[0,1,0]
	v_pk_fma_f32 v[14:15], v[194:195], v[58:59], v[14:15] op_sel_hi:[1,0,1]
	v_pk_fma_f32 v[16:17], v[196:197], v[58:59], v[16:17] op_sel_hi:[1,0,1]
	v_pk_fma_f32 v[18:19], v[194:195], v[58:59], v[18:19] op_sel:[0,1,0]
	v_pk_fma_f32 v[20:21], v[196:197], v[58:59], v[20:21] op_sel:[0,1,0]
	v_pk_fma_f32 v[22:23], v[194:195], v[60:61], v[22:23] op_sel_hi:[1,0,1]
	v_pk_fma_f32 v[24:25], v[196:197], v[60:61], v[24:25] op_sel_hi:[1,0,1]
	v_pk_fma_f32 v[26:27], v[194:195], v[60:61], v[26:27] op_sel:[0,1,0]
	v_pk_fma_f32 v[28:29], v[196:197], v[60:61], v[28:29] op_sel:[0,1,0]
	s_waitcnt vmcnt(13)
	v_pk_fma_f32 v[10:11], v[198:199], v[62:63], v[10:11] op_sel_hi:[1,0,1]
	v_pk_fma_f32 v[12:13], v[200:201], v[62:63], v[12:13] op_sel_hi:[1,0,1]
	v_pk_fma_f32 v[14:15], v[198:199], v[62:63], v[14:15] op_sel:[0,1,0]
	v_pk_fma_f32 v[16:17], v[200:201], v[62:63], v[16:17] op_sel:[0,1,0]
	v_pk_fma_f32 v[18:19], v[198:199], v[64:65], v[18:19] op_sel_hi:[1,0,1]
	v_pk_fma_f32 v[20:21], v[200:201], v[64:65], v[20:21] op_sel_hi:[1,0,1]
	v_pk_fma_f32 v[22:23], v[198:199], v[64:65], v[22:23] op_sel:[0,1,0]
	v_pk_fma_f32 v[24:25], v[200:201], v[64:65], v[24:25] op_sel:[0,1,0]
	v_pk_fma_f32 v[26:27], v[198:199], v[66:67], v[26:27] op_sel_hi:[1,0,1]
	v_pk_fma_f32 v[28:29], v[200:201], v[66:67], v[28:29] op_sel_hi:[1,0,1]
	s_waitcnt vmcnt(12)
	v_pk_fma_f32 v[10:11], v[202:203], v[66:67], v[10:11] op_sel:[0,1,0]
	v_pk_fma_f32 v[12:13], v[204:205], v[66:67], v[12:13] op_sel:[0,1,0]
	v_pk_fma_f32 v[14:15], v[202:203], v[68:69], v[14:15] op_sel_hi:[1,0,1]
	v_pk_fma_f32 v[16:17], v[204:205], v[68:69], v[16:17] op_sel_hi:[1,0,1]
	v_pk_fma_f32 v[18:19], v[202:203], v[68:69], v[18:19] op_sel:[0,1,0]
	v_pk_fma_f32 v[20:21], v[204:205], v[68:69], v[20:21] op_sel:[0,1,0]
	v_pk_fma_f32 v[22:23], v[202:203], v[70:71], v[22:23] op_sel_hi:[1,0,1]
	v_pk_fma_f32 v[24:25], v[204:205], v[70:71], v[24:25] op_sel_hi:[1,0,1]
	v_pk_fma_f32 v[26:27], v[202:203], v[70:71], v[26:27] op_sel:[0,1,0]
	v_pk_fma_f32 v[28:29], v[204:205], v[70:71], v[28:29] op_sel:[0,1,0]
	ds_read_b32 v52, v34 offset:2560
	ds_read_b32 v53, v34 offset:6656
	ds_read_b32 v54, v34 offset:10752
	ds_read_b32 v55, v34 offset:14848
	ds_read_b32 v56, v34 offset:18944
	ds_read_b32 v57, v34 offset:2688
	ds_read_b32 v58, v34 offset:6784
	ds_read_b32 v59, v34 offset:10880
	ds_read_b32 v60, v34 offset:14976
	ds_read_b32 v61, v34 offset:19072
	ds_read_b32 v62, v34 offset:2816
	ds_read_b32 v63, v34 offset:6912
	ds_read_b32 v64, v34 offset:11008
	ds_read_b32 v65, v34 offset:15104
	ds_read_b32 v66, v34 offset:19200
	ds_read_b32 v67, v34 offset:2944
	ds_read_b32 v68, v34 offset:7040
	ds_read_b32 v69, v34 offset:11136
	ds_read_b32 v70, v34 offset:15232
	ds_read_b32 v71, v34 offset:19328
	s_waitcnt lgkmcnt(0)
	s_waitcnt vmcnt(11)
	v_pk_fma_f32 v[10:11], v[206:207], v[52:53], v[10:11] op_sel_hi:[1,0,1]
	v_pk_fma_f32 v[12:13], v[208:209], v[52:53], v[12:13] op_sel_hi:[1,0,1]
	v_pk_fma_f32 v[14:15], v[206:207], v[52:53], v[14:15] op_sel:[0,1,0]
	v_pk_fma_f32 v[16:17], v[208:209], v[52:53], v[16:17] op_sel:[0,1,0]
	v_pk_fma_f32 v[18:19], v[206:207], v[54:55], v[18:19] op_sel_hi:[1,0,1]
	v_pk_fma_f32 v[20:21], v[208:209], v[54:55], v[20:21] op_sel_hi:[1,0,1]
	v_pk_fma_f32 v[22:23], v[206:207], v[54:55], v[22:23] op_sel:[0,1,0]
	v_pk_fma_f32 v[24:25], v[208:209], v[54:55], v[24:25] op_sel:[0,1,0]
	v_pk_fma_f32 v[26:27], v[206:207], v[56:57], v[26:27] op_sel_hi:[1,0,1]
	v_pk_fma_f32 v[28:29], v[208:209], v[56:57], v[28:29] op_sel_hi:[1,0,1]
	s_waitcnt vmcnt(10)
	v_pk_fma_f32 v[10:11], v[210:211], v[56:57], v[10:11] op_sel:[0,1,0]
	v_pk_fma_f32 v[12:13], v[212:213], v[56:57], v[12:13] op_sel:[0,1,0]
	v_pk_fma_f32 v[14:15], v[210:211], v[58:59], v[14:15] op_sel_hi:[1,0,1]
	v_pk_fma_f32 v[16:17], v[212:213], v[58:59], v[16:17] op_sel_hi:[1,0,1]
	v_pk_fma_f32 v[18:19], v[210:211], v[58:59], v[18:19] op_sel:[0,1,0]
	v_pk_fma_f32 v[20:21], v[212:213], v[58:59], v[20:21] op_sel:[0,1,0]
	v_pk_fma_f32 v[22:23], v[210:211], v[60:61], v[22:23] op_sel_hi:[1,0,1]
	v_pk_fma_f32 v[24:25], v[212:213], v[60:61], v[24:25] op_sel_hi:[1,0,1]
	v_pk_fma_f32 v[26:27], v[210:211], v[60:61], v[26:27] op_sel:[0,1,0]
	v_pk_fma_f32 v[28:29], v[212:213], v[60:61], v[28:29] op_sel:[0,1,0]
	s_waitcnt vmcnt(9)
	v_pk_fma_f32 v[10:11], v[214:215], v[62:63], v[10:11] op_sel_hi:[1,0,1]
	v_pk_fma_f32 v[12:13], v[216:217], v[62:63], v[12:13] op_sel_hi:[1,0,1]
	v_pk_fma_f32 v[14:15], v[214:215], v[62:63], v[14:15] op_sel:[0,1,0]
	v_pk_fma_f32 v[16:17], v[216:217], v[62:63], v[16:17] op_sel:[0,1,0]
	v_pk_fma_f32 v[18:19], v[214:215], v[64:65], v[18:19] op_sel_hi:[1,0,1]
	v_pk_fma_f32 v[20:21], v[216:217], v[64:65], v[20:21] op_sel_hi:[1,0,1]
	v_pk_fma_f32 v[22:23], v[214:215], v[64:65], v[22:23] op_sel:[0,1,0]
	v_pk_fma_f32 v[24:25], v[216:217], v[64:65], v[24:25] op_sel:[0,1,0]
	v_pk_fma_f32 v[26:27], v[214:215], v[66:67], v[26:27] op_sel_hi:[1,0,1]
	v_pk_fma_f32 v[28:29], v[216:217], v[66:67], v[28:29] op_sel_hi:[1,0,1]
	s_waitcnt vmcnt(8)
	v_pk_fma_f32 v[10:11], v[218:219], v[66:67], v[10:11] op_sel:[0,1,0]
	v_pk_fma_f32 v[12:13], v[220:221], v[66:67], v[12:13] op_sel:[0,1,0]
	v_pk_fma_f32 v[14:15], v[218:219], v[68:69], v[14:15] op_sel_hi:[1,0,1]
	v_pk_fma_f32 v[16:17], v[220:221], v[68:69], v[16:17] op_sel_hi:[1,0,1]
	v_pk_fma_f32 v[18:19], v[218:219], v[68:69], v[18:19] op_sel:[0,1,0]
	v_pk_fma_f32 v[20:21], v[220:221], v[68:69], v[20:21] op_sel:[0,1,0]
	v_pk_fma_f32 v[22:23], v[218:219], v[70:71], v[22:23] op_sel_hi:[1,0,1]
	v_pk_fma_f32 v[24:25], v[220:221], v[70:71], v[24:25] op_sel_hi:[1,0,1]
	v_pk_fma_f32 v[26:27], v[218:219], v[70:71], v[26:27] op_sel:[0,1,0]
	v_pk_fma_f32 v[28:29], v[220:221], v[70:71], v[28:29] op_sel:[0,1,0]
	ds_read_b32 v52, v34 offset:3072
	ds_read_b32 v53, v34 offset:7168
	ds_read_b32 v54, v34 offset:11264
	ds_read_b32 v55, v34 offset:15360
	ds_read_b32 v56, v34 offset:19456
	ds_read_b32 v57, v34 offset:3200
	ds_read_b32 v58, v34 offset:7296
	ds_read_b32 v59, v34 offset:11392
	ds_read_b32 v60, v34 offset:15488
	ds_read_b32 v61, v34 offset:19584
	ds_read_b32 v62, v34 offset:3328
	ds_read_b32 v63, v34 offset:7424
	ds_read_b32 v64, v34 offset:11520
	ds_read_b32 v65, v34 offset:15616
	ds_read_b32 v66, v34 offset:19712
	ds_read_b32 v67, v34 offset:3456
	ds_read_b32 v68, v34 offset:7552
	ds_read_b32 v69, v34 offset:11648
	ds_read_b32 v70, v34 offset:15744
	ds_read_b32 v71, v34 offset:19840
	s_waitcnt lgkmcnt(0)
	s_waitcnt vmcnt(7)
	v_pk_fma_f32 v[10:11], v[222:223], v[52:53], v[10:11] op_sel_hi:[1,0,1]
	v_pk_fma_f32 v[12:13], v[224:225], v[52:53], v[12:13] op_sel_hi:[1,0,1]
	v_pk_fma_f32 v[14:15], v[222:223], v[52:53], v[14:15] op_sel:[0,1,0]
	v_pk_fma_f32 v[16:17], v[224:225], v[52:53], v[16:17] op_sel:[0,1,0]
	v_pk_fma_f32 v[18:19], v[222:223], v[54:55], v[18:19] op_sel_hi:[1,0,1]
	v_pk_fma_f32 v[20:21], v[224:225], v[54:55], v[20:21] op_sel_hi:[1,0,1]
	v_pk_fma_f32 v[22:23], v[222:223], v[54:55], v[22:23] op_sel:[0,1,0]
	v_pk_fma_f32 v[24:25], v[224:225], v[54:55], v[24:25] op_sel:[0,1,0]
	v_pk_fma_f32 v[26:27], v[222:223], v[56:57], v[26:27] op_sel_hi:[1,0,1]
	v_pk_fma_f32 v[28:29], v[224:225], v[56:57], v[28:29] op_sel_hi:[1,0,1]
	s_waitcnt vmcnt(6)
	v_pk_fma_f32 v[10:11], v[226:227], v[56:57], v[10:11] op_sel:[0,1,0]
	v_pk_fma_f32 v[12:13], v[228:229], v[56:57], v[12:13] op_sel:[0,1,0]
	v_pk_fma_f32 v[14:15], v[226:227], v[58:59], v[14:15] op_sel_hi:[1,0,1]
	v_pk_fma_f32 v[16:17], v[228:229], v[58:59], v[16:17] op_sel_hi:[1,0,1]
	v_pk_fma_f32 v[18:19], v[226:227], v[58:59], v[18:19] op_sel:[0,1,0]
	v_pk_fma_f32 v[20:21], v[228:229], v[58:59], v[20:21] op_sel:[0,1,0]
	v_pk_fma_f32 v[22:23], v[226:227], v[60:61], v[22:23] op_sel_hi:[1,0,1]
	v_pk_fma_f32 v[24:25], v[228:229], v[60:61], v[24:25] op_sel_hi:[1,0,1]
	v_pk_fma_f32 v[26:27], v[226:227], v[60:61], v[26:27] op_sel:[0,1,0]
	v_pk_fma_f32 v[28:29], v[228:229], v[60:61], v[28:29] op_sel:[0,1,0]
	s_waitcnt vmcnt(5)
	v_pk_fma_f32 v[10:11], v[230:231], v[62:63], v[10:11] op_sel_hi:[1,0,1]
	v_pk_fma_f32 v[12:13], v[232:233], v[62:63], v[12:13] op_sel_hi:[1,0,1]
	v_pk_fma_f32 v[14:15], v[230:231], v[62:63], v[14:15] op_sel:[0,1,0]
	v_pk_fma_f32 v[16:17], v[232:233], v[62:63], v[16:17] op_sel:[0,1,0]
	v_pk_fma_f32 v[18:19], v[230:231], v[64:65], v[18:19] op_sel_hi:[1,0,1]
	v_pk_fma_f32 v[20:21], v[232:233], v[64:65], v[20:21] op_sel_hi:[1,0,1]
	v_pk_fma_f32 v[22:23], v[230:231], v[64:65], v[22:23] op_sel:[0,1,0]
	v_pk_fma_f32 v[24:25], v[232:233], v[64:65], v[24:25] op_sel:[0,1,0]
	v_pk_fma_f32 v[26:27], v[230:231], v[66:67], v[26:27] op_sel_hi:[1,0,1]
	v_pk_fma_f32 v[28:29], v[232:233], v[66:67], v[28:29] op_sel_hi:[1,0,1]
	s_waitcnt vmcnt(4)
	v_pk_fma_f32 v[10:11], v[234:235], v[66:67], v[10:11] op_sel:[0,1,0]
	v_pk_fma_f32 v[12:13], v[236:237], v[66:67], v[12:13] op_sel:[0,1,0]
	v_pk_fma_f32 v[14:15], v[234:235], v[68:69], v[14:15] op_sel_hi:[1,0,1]
	v_pk_fma_f32 v[16:17], v[236:237], v[68:69], v[16:17] op_sel_hi:[1,0,1]
	v_pk_fma_f32 v[18:19], v[234:235], v[68:69], v[18:19] op_sel:[0,1,0]
	v_pk_fma_f32 v[20:21], v[236:237], v[68:69], v[20:21] op_sel:[0,1,0]
	v_pk_fma_f32 v[22:23], v[234:235], v[70:71], v[22:23] op_sel_hi:[1,0,1]
	v_pk_fma_f32 v[24:25], v[236:237], v[70:71], v[24:25] op_sel_hi:[1,0,1]
	v_pk_fma_f32 v[26:27], v[234:235], v[70:71], v[26:27] op_sel:[0,1,0]
	v_pk_fma_f32 v[28:29], v[236:237], v[70:71], v[28:29] op_sel:[0,1,0]
	ds_read_b32 v52, v34 offset:3584
	ds_read_b32 v53, v34 offset:7680
	ds_read_b32 v54, v34 offset:11776
	ds_read_b32 v55, v34 offset:15872
	ds_read_b32 v56, v34 offset:19968
	ds_read_b32 v57, v34 offset:3712
	ds_read_b32 v58, v34 offset:7808
	ds_read_b32 v59, v34 offset:11904
	ds_read_b32 v60, v34 offset:16000
	ds_read_b32 v61, v34 offset:20096
	ds_read_b32 v62, v34 offset:3840
	ds_read_b32 v63, v34 offset:7936
	ds_read_b32 v64, v34 offset:12032
	ds_read_b32 v65, v34 offset:16128
	ds_read_b32 v66, v34 offset:20224
	ds_read_b32 v67, v34 offset:3968
	ds_read_b32 v68, v34 offset:8064
	ds_read_b32 v69, v34 offset:12160
	ds_read_b32 v70, v34 offset:16256
	ds_read_b32 v71, v34 offset:20352
	s_waitcnt lgkmcnt(0)
	s_waitcnt vmcnt(3)
	v_pk_fma_f32 v[10:11], v[238:239], v[52:53], v[10:11] op_sel_hi:[1,0,1]
	v_pk_fma_f32 v[12:13], v[240:241], v[52:53], v[12:13] op_sel_hi:[1,0,1]
	v_pk_fma_f32 v[14:15], v[238:239], v[52:53], v[14:15] op_sel:[0,1,0]
	v_pk_fma_f32 v[16:17], v[240:241], v[52:53], v[16:17] op_sel:[0,1,0]
	v_pk_fma_f32 v[18:19], v[238:239], v[54:55], v[18:19] op_sel_hi:[1,0,1]
	v_pk_fma_f32 v[20:21], v[240:241], v[54:55], v[20:21] op_sel_hi:[1,0,1]
	v_pk_fma_f32 v[22:23], v[238:239], v[54:55], v[22:23] op_sel:[0,1,0]
	v_pk_fma_f32 v[24:25], v[240:241], v[54:55], v[24:25] op_sel:[0,1,0]
	v_pk_fma_f32 v[26:27], v[238:239], v[56:57], v[26:27] op_sel_hi:[1,0,1]
	v_pk_fma_f32 v[28:29], v[240:241], v[56:57], v[28:29] op_sel_hi:[1,0,1]
	s_waitcnt vmcnt(2)
	v_pk_fma_f32 v[10:11], v[242:243], v[56:57], v[10:11] op_sel:[0,1,0]
	v_pk_fma_f32 v[12:13], v[244:245], v[56:57], v[12:13] op_sel:[0,1,0]
	v_pk_fma_f32 v[14:15], v[242:243], v[58:59], v[14:15] op_sel_hi:[1,0,1]
	v_pk_fma_f32 v[16:17], v[244:245], v[58:59], v[16:17] op_sel_hi:[1,0,1]
	v_pk_fma_f32 v[18:19], v[242:243], v[58:59], v[18:19] op_sel:[0,1,0]
	v_pk_fma_f32 v[20:21], v[244:245], v[58:59], v[20:21] op_sel:[0,1,0]
	v_pk_fma_f32 v[22:23], v[242:243], v[60:61], v[22:23] op_sel_hi:[1,0,1]
	v_pk_fma_f32 v[24:25], v[244:245], v[60:61], v[24:25] op_sel_hi:[1,0,1]
	v_pk_fma_f32 v[26:27], v[242:243], v[60:61], v[26:27] op_sel:[0,1,0]
	v_pk_fma_f32 v[28:29], v[244:245], v[60:61], v[28:29] op_sel:[0,1,0]
	s_waitcnt vmcnt(1)
	v_pk_fma_f32 v[10:11], v[246:247], v[62:63], v[10:11] op_sel_hi:[1,0,1]
	v_pk_fma_f32 v[12:13], v[248:249], v[62:63], v[12:13] op_sel_hi:[1,0,1]
	v_pk_fma_f32 v[14:15], v[246:247], v[62:63], v[14:15] op_sel:[0,1,0]
	v_pk_fma_f32 v[16:17], v[248:249], v[62:63], v[16:17] op_sel:[0,1,0]
	v_pk_fma_f32 v[18:19], v[246:247], v[64:65], v[18:19] op_sel_hi:[1,0,1]
	v_pk_fma_f32 v[20:21], v[248:249], v[64:65], v[20:21] op_sel_hi:[1,0,1]
	v_pk_fma_f32 v[22:23], v[246:247], v[64:65], v[22:23] op_sel:[0,1,0]
	v_pk_fma_f32 v[24:25], v[248:249], v[64:65], v[24:25] op_sel:[0,1,0]
	v_pk_fma_f32 v[26:27], v[246:247], v[66:67], v[26:27] op_sel_hi:[1,0,1]
	v_pk_fma_f32 v[28:29], v[248:249], v[66:67], v[28:29] op_sel_hi:[1,0,1]
	s_waitcnt vmcnt(0)
	v_pk_fma_f32 v[10:11], v[250:251], v[66:67], v[10:11] op_sel:[0,1,0]
	v_pk_fma_f32 v[12:13], v[252:253], v[66:67], v[12:13] op_sel:[0,1,0]
	v_pk_fma_f32 v[14:15], v[250:251], v[68:69], v[14:15] op_sel_hi:[1,0,1]
	v_pk_fma_f32 v[16:17], v[252:253], v[68:69], v[16:17] op_sel_hi:[1,0,1]
	v_pk_fma_f32 v[18:19], v[250:251], v[68:69], v[18:19] op_sel:[0,1,0]
	v_pk_fma_f32 v[20:21], v[252:253], v[68:69], v[20:21] op_sel:[0,1,0]
	v_pk_fma_f32 v[22:23], v[250:251], v[70:71], v[22:23] op_sel_hi:[1,0,1]
	v_pk_fma_f32 v[24:25], v[252:253], v[70:71], v[24:25] op_sel_hi:[1,0,1]
	v_pk_fma_f32 v[26:27], v[250:251], v[70:71], v[26:27] op_sel:[0,1,0]
	v_pk_fma_f32 v[28:29], v[252:253], v[70:71], v[28:29] op_sel:[0,1,0]
	ds_write_b128 v35, v[10:13] offset:20480
	ds_write_b128 v35, v[14:17] offset:20736
	ds_write_b128 v35, v[18:21] offset:20992
	ds_write_b128 v35, v[22:25] offset:21248
	ds_write_b128 v35, v[26:29] offset:21504
	s_waitcnt lgkmcnt(0)
	s_barrier
	v_cmp_gt_u32_e32 vcc, 0x50, v102
	s_and_saveexec_b64 s[28:29], vcc
	s_cbranch_execz .Lad_red_done
	v_lshlrev_b32_e32 v36, 4, v102
	v_lshrrev_b32_e32 v37, 4, v102
	v_lshlrev_b32_e32 v38, 4, v31
	s_mul_i32 s30, s24, 0x6000
	s_lshl_b32 s31, s25, 2
	s_add_u32 s30, s30, s31
	s_add_u32 s32, s38, s30
	s_addc_u32 s33, s39, 0
	global_load_dwordx4 v[10:13], v38, s[32:33]
	ds_read_b128 v[130:133], v36 offset:20480
	ds_read_b128 v[134:137], v36 offset:21760
	ds_read_b128 v[138:141], v36 offset:23040
	ds_read_b128 v[142:145], v36 offset:24320
	ds_read_b128 v[146:149], v36 offset:25600
	ds_read_b128 v[150:153], v36 offset:26880
	ds_read_b128 v[154:157], v36 offset:28160
	ds_read_b128 v[158:161], v36 offset:29440
	s_waitcnt lgkmcnt(0)
	s_waitcnt vmcnt(0)
	v_add_f32_e32 v10, v10, v130
	v_add_f32_e32 v11, v11, v131
	v_add_f32_e32 v12, v12, v132
	v_add_f32_e32 v13, v13, v133
	v_add_f32_e32 v10, v10, v134
	v_add_f32_e32 v11, v11, v135
	v_add_f32_e32 v12, v12, v136
	v_add_f32_e32 v13, v13, v137
	v_add_f32_e32 v10, v10, v138
	v_add_f32_e32 v11, v11, v139
	v_add_f32_e32 v12, v12, v140
	v_add_f32_e32 v13, v13, v141
	v_add_f32_e32 v10, v10, v142
	v_add_f32_e32 v11, v11, v143
	v_add_f32_e32 v12, v12, v144
	v_add_f32_e32 v13, v13, v145
	v_add_f32_e32 v10, v10, v146
	v_add_f32_e32 v11, v11, v147
	v_add_f32_e32 v12, v12, v148
	v_add_f32_e32 v13, v13, v149
	v_add_f32_e32 v10, v10, v150
	v_add_f32_e32 v11, v11, v151
	v_add_f32_e32 v12, v12, v152
	v_add_f32_e32 v13, v13, v153
	v_add_f32_e32 v10, v10, v154
	v_add_f32_e32 v11, v11, v155
	v_add_f32_e32 v12, v12, v156
	v_add_f32_e32 v13, v13, v157
	v_add_f32_e32 v10, v10, v158
	v_add_f32_e32 v11, v11, v159
	v_add_f32_e32 v12, v12, v160
	v_add_f32_e32 v13, v13, v161
	ds_read_b128 v[130:133], v36 offset:30720
	ds_read_b128 v[134:137], v36 offset:32000
	ds_read_b128 v[138:141], v36 offset:33280
	ds_read_b128 v[142:145], v36 offset:34560
	ds_read_b128 v[146:149], v36 offset:35840
	ds_read_b128 v[150:153], v36 offset:37120
	ds_read_b128 v[154:157], v36 offset:38400
	ds_read_b128 v[158:161], v36 offset:39680
	s_waitcnt lgkmcnt(0)
	v_add_f32_e32 v10, v10, v130
	v_add_f32_e32 v11, v11, v131
	v_add_f32_e32 v12, v12, v132
	v_add_f32_e32 v13, v13, v133
	v_add_f32_e32 v10, v10, v134
	v_add_f32_e32 v11, v11, v135
	v_add_f32_e32 v12, v12, v136
	v_add_f32_e32 v13, v13, v137
	v_add_f32_e32 v10, v10, v138
	v_add_f32_e32 v11, v11, v139
	v_add_f32_e32 v12, v12, v140
	v_add_f32_e32 v13, v13, v141
	v_add_f32_e32 v10, v10, v142
	v_add_f32_e32 v11, v11, v143
	v_add_f32_e32 v12, v12, v144
	v_add_f32_e32 v13, v13, v145
	v_add_f32_e32 v10, v10, v146
	v_add_f32_e32 v11, v11, v147
	v_add_f32_e32 v12, v12, v148
	v_add_f32_e32 v13, v13, v149
	v_add_f32_e32 v10, v10, v150
	v_add_f32_e32 v11, v11, v151
	v_add_f32_e32 v12, v12, v152
	v_add_f32_e32 v13, v13, v153
	v_add_f32_e32 v10, v10, v154
	v_add_f32_e32 v11, v11, v155
	v_add_f32_e32 v12, v12, v156
	v_add_f32_e32 v13, v13, v157
	v_add_f32_e32 v10, v10, v158
	v_add_f32_e32 v11, v11, v159
	v_add_f32_e32 v12, v12, v160
	v_add_f32_e32 v13, v13, v161
	ds_read_b128 v[130:133], v36 offset:40960
	ds_read_b128 v[134:137], v36 offset:42240
	ds_read_b128 v[138:141], v36 offset:43520
	ds_read_b128 v[142:145], v36 offset:44800
	ds_read_b128 v[146:149], v36 offset:46080
	ds_read_b128 v[150:153], v36 offset:47360
	ds_read_b128 v[154:157], v36 offset:48640
	ds_read_b128 v[158:161], v36 offset:49920
	s_waitcnt lgkmcnt(0)
	v_add_f32_e32 v10, v10, v130
	v_add_f32_e32 v11, v11, v131
	v_add_f32_e32 v12, v12, v132
	v_add_f32_e32 v13, v13, v133
	v_add_f32_e32 v10, v10, v134
	v_add_f32_e32 v11, v11, v135
	v_add_f32_e32 v12, v12, v136
	v_add_f32_e32 v13, v13, v137
	v_add_f32_e32 v10, v10, v138
	v_add_f32_e32 v11, v11, v139
	v_add_f32_e32 v12, v12, v140
	v_add_f32_e32 v13, v13, v141
	v_add_f32_e32 v10, v10, v142
	v_add_f32_e32 v11, v11, v143
	v_add_f32_e32 v12, v12, v144
	v_add_f32_e32 v13, v13, v145
	v_add_f32_e32 v10, v10, v146
	v_add_f32_e32 v11, v11, v147
	v_add_f32_e32 v12, v12, v148
	v_add_f32_e32 v13, v13, v149
	v_add_f32_e32 v10, v10, v150
	v_add_f32_e32 v11, v11, v151
	v_add_f32_e32 v12, v12, v152
	v_add_f32_e32 v13, v13, v153
	v_add_f32_e32 v10, v10, v154
	v_add_f32_e32 v11, v11, v155
	v_add_f32_e32 v12, v12, v156
	v_add_f32_e32 v13, v13, v157
	v_add_f32_e32 v10, v10, v158
	v_add_f32_e32 v11, v11, v159
	v_add_f32_e32 v12, v12, v160
	v_add_f32_e32 v13, v13, v161
	ds_read_b128 v[130:133], v36 offset:51200
	ds_read_b128 v[134:137], v36 offset:52480
	ds_read_b128 v[138:141], v36 offset:53760
	ds_read_b128 v[142:145], v36 offset:55040
	ds_read_b128 v[146:149], v36 offset:56320
	ds_read_b128 v[150:153], v36 offset:57600
	ds_read_b128 v[154:157], v36 offset:58880
	ds_read_b128 v[158:161], v36 offset:60160
	s_waitcnt lgkmcnt(0)
	v_add_f32_e32 v10, v10, v130
	v_add_f32_e32 v11, v11, v131
	v_add_f32_e32 v12, v12, v132
	v_add_f32_e32 v13, v13, v133
	v_add_f32_e32 v10, v10, v134
	v_add_f32_e32 v11, v11, v135
	v_add_f32_e32 v12, v12, v136
	v_add_f32_e32 v13, v13, v137
	v_add_f32_e32 v10, v10, v138
	v_add_f32_e32 v11, v11, v139
	v_add_f32_e32 v12, v12, v140
	v_add_f32_e32 v13, v13, v141
	v_add_f32_e32 v10, v10, v142
	v_add_f32_e32 v11, v11, v143
	v_add_f32_e32 v12, v12, v144
	v_add_f32_e32 v13, v13, v145
	v_add_f32_e32 v10, v10, v146
	v_add_f32_e32 v11, v11, v147
	v_add_f32_e32 v12, v12, v148
	v_add_f32_e32 v13, v13, v149
	v_add_f32_e32 v10, v10, v150
	v_add_f32_e32 v11, v11, v151
	v_add_f32_e32 v12, v12, v152
	v_add_f32_e32 v13, v13, v153
	v_add_f32_e32 v10, v10, v154
	v_add_f32_e32 v11, v11, v155
	v_add_f32_e32 v12, v12, v156
	v_add_f32_e32 v13, v13, v157
	v_add_f32_e32 v10, v10, v158
	v_add_f32_e32 v11, v11, v159
	v_add_f32_e32 v12, v12, v160
	v_add_f32_e32 v13, v13, v161
	s_mul_i32 s30, s24, 5
	v_add_u32_e32 v37, s30, v37
	v_mul_u32_u24_e32 v37, 0x6000, v37
	v_add_u32_e32 v37, v37, v38
	v_add_u32_e32 v37, s31, v37
	s_add_u32 s34, s20, 0x10000
	s_addc_u32 s35, s21, 0
	global_store_dwordx4 v37, v[10:13], s[34:35]
.Lad_red_done:
	s_or_b64 exec, exec, s[28:29]
	s_barrier
	s_cmp_eq_u32 s98, 2
	s_cbranch_scc1 .Lfw_after
.Lad_skip:
	v_cvt_f32_i32_e32 v121, v102
	s_cmpk_gt_i32 s93, 0x15f
	v_lshl_add_u32 v115, v102, 3, 0
	v_ashrrev_i32_e32 v120, 2, v102
	s_cbranch_scc1 .LBB0_51
	s_cmp_eq_u32 s101, 1
	s_cbranch_scc1 .LBB0_51
	s_add_u32 s22, s20, 0x10000
	s_addc_u32 s23, s21, 0
	s_cmpk_lt_i32 s74, 0x100
	v_max_i32_e32 v9, 0x600, v102
	s_cselect_b64 s[24:25], -1, 0
	s_cmpk_gt_i32 s74, 0xff
	v_sub_u32_e32 v9, v9, v102
	s_cselect_b64 s[0:1], -1, 0
	s_cmpk_lt_i32 s93, 0x60
	v_add_u32_e32 v9, 0x1ff, v9
	s_cselect_b64 s[8:9], -1, 0
	s_add_u32 s26, s20, 0x380000
	v_lshrrev_b32_e32 v11, 9, v9
	s_addc_u32 s27, s21, 0
	s_movk_i32 s2, 0x800
	v_mul_f32_e32 v2, 0x3c000000, v121
	s_and_b64 s[30:31], s[0:1], s[8:9]
	s_movk_i32 s0, 0x1ff
	v_add_u32_e32 v13, 1, v11
	v_add_u32_e32 v11, -1, v11
	v_cmp_gt_i32_e64 s[16:17], s2, v102
	s_movk_i32 s2, 0x80
	v_cos_f32_e32 v108, v2
	v_sin_f32_e32 v109, v2
	v_ashrrev_i32_e32 v130, 5, v102
	v_lshrrev_b32_e32 v14, 1, v11
	v_cmp_lt_u32_e64 s[8:9], s0, v9
	v_and_b32_e32 v9, 0xfffffe, v13
	v_cmp_gt_i32_e64 s[4:5], s2, v102
	v_add_u32_e32 v103, 0x200, v102
	v_add_u32_e32 v126, 0x600, v102
	s_movk_i32 s2, 0xa00
	v_add_u32_e32 v127, 0xa00, v102
	v_add_u32_e32 v128, 0xe00, v102
	v_add_u32_e32 v129, 0x1200, v102
	v_and_b32_e32 v3, 31, v105
	v_lshlrev_b32_e32 v5, 6, v130
	s_movk_i32 s33, 0x6000
	v_add_u32_e32 v14, 1, v14
	v_lshl_add_u32 v133, v9, 9, v102
	v_cmp_ne_u32_e64 s[14:15], v13, v9
	v_lshrrev_b32_e32 v9, 2, v120
	v_and_b32_e32 v104, 15, v105
	v_and_b32_e32 v110, -4, v120
	v_or_b32_e32 v123, 3, v120
	v_lshlrev_b32_e32 v124, 2, v102
	v_and_b32_e32 v2, 0x3ff, v102
	v_and_b32_e32 v4, 0x3ff, v103
	v_and_b32_e32 v6, 0x3ff, v126
	v_and_b32_e32 v8, 0x3ff, v127
	v_and_b32_e32 v10, 0x3ff, v128
	v_and_b32_e32 v12, 0x3ff, v129
	v_mad_i64_i32 v[112:113], s[6:7], v5, s33, 0
	v_lshlrev_b32_e32 v114, 2, v3
	v_lshl_add_u32 v3, v3, 4, 0
	v_mul_lo_u32 v5, v130, s2
	s_movk_i32 s2, 0xa0
	v_lshlrev_b32_e32 v7, 9, v130
	v_and_b32_e32 v223, 3, v14
	v_lshlrev_b32_e32 v136, 4, v9
	v_mul_lo_u32 v139, v9, 12
	v_lshlrev_b32_e32 v141, 3, v9
	v_mov_b32_e32 v107, 0
	s_mov_b32 s29, 0
	v_lshl_add_u32 v122, v104, 2, 0
	v_ashrrev_i32_e32 v111, 31, v110
	v_sub_u32_e32 v125, v115, v124
	v_lshl_add_u32 v131, v130, 8, 0
	v_cmp_gt_i32_e64 s[6:7], s2, v102
	v_cmp_lt_u32_e64 s[10:11], 5, v11
	v_and_b32_e32 v135, -4, v14
	v_cmp_ne_u32_e64 s[12:13], 0, v223
	v_add_u32_e32 v221, 0, v124
	v_or_b32_e32 v137, 4, v136
	v_or_b32_e32 v138, 8, v136
	v_or_b32_e32 v140, 3, v139
	v_or_b32_e32 v142, 2, v141
	v_or_b32_e32 v143, 1, v110
	v_lshlrev_b32_e32 v144, 2, v123
	v_lshlrev_b32_e32 v145, 1, v123
	v_lshl_add_u32 v146, v123, 1, v123
	s_movk_i32 s35, 0x5ff
	s_mov_b32 s34, 0x3db504f3
	v_lshlrev_b32_e32 v147, 2, v2
	v_lshlrev_b32_e32 v148, 2, v4
	v_lshlrev_b32_e32 v149, 2, v6
	v_lshlrev_b32_e32 v150, 2, v8
	v_lshlrev_b32_e32 v151, 2, v10
	v_lshlrev_b32_e32 v152, 2, v12
	s_mov_b32 s46, 0xc000
	s_mov_b32 s47, 0x12000
	s_mov_b32 s48, 0x18000
	s_mov_b32 s49, 0x1e000
	s_mov_b32 s50, 0x24000
	s_mov_b32 s51, 0x2a000
	s_mov_b32 s52, 0x30000
	s_mov_b32 s53, 0x36000
	s_mov_b32 s54, 0x3c000
	s_mov_b32 s55, 0x42000
	s_mov_b32 s56, 0x48000
	s_mov_b32 s57, 0x4e000
	s_mov_b32 s58, 0x54000
	s_mov_b32 s59, 0x5a000
	v_add_u32_e32 v153, v3, v5
	v_add_u32_e32 v154, v3, v7
	s_mov_b32 s60, s93
	s_branch .LBB0_20

.LBB0_51:
	s_lshr_b32 s64, s68, 6
	s_cmpk_lt_i32 s74, 0x100
	s_cselect_b64 s[0:1], -1, 0
	s_add_i32 s2, s93, 0xfffffea0
	s_cmp_lt_u32 s2, 0xffffff00
	s_cselect_b64 s[4:5], -1, 0
	s_or_b64 s[0:1], s[4:5], s[0:1]
	s_and_b64 vcc, exec, s[0:1]
	s_cmp_eq_u32 s101, 1
	s_cbranch_scc1 .Lfw_all
	s_cbranch_vccnz .LBB0_71
.Lfw_all:
	v_cvt_f32_i32_e32 v130, v102
	v_mul_f32_e32 v130, 0x3c000000, v130
	v_cos_f32_e32 v184, v130
	v_sin_f32_e32 v185, v130
	v_lshrrev_b32_e32 v130, 6, v102
	v_bfe_u32 v131, v102, 2, 4
	v_and_b32_e32 v132, 3, v102
	v_bfe_u32 v133, v102, 3, 3
	v_and_b32_e32 v134, 7, v102
	v_lshlrev_b32_e32 v135, 7, v132
	v_lshlrev_b32_e32 v136, 6, v134
	v_lshlrev_b32_e32 v137, 10, v130
	v_lshl_add_u32 v137, v131, 3, v137
	v_lshl_add_u32 v138, v130, 3, v133
	v_mul_u32_u24_e32 v138, 0x88, v138
	v_add_u32_e32 v138, 0x3000, v138
	v_lshl_add_u32 v139, v130, 3, v132
	v_mul_u32_u24_e32 v139, 0x88, v139
	v_lshl_add_u32 v139, v131, 3, v139
	v_mul_u32_u24_e32 v140, v131, v132
	v_lshl_add_u32 v141, v131, 2, v140
	v_lshlrev_b32_e32 v140, 3, v140
	v_lshlrev_b32_e32 v141, 3, v141
	v_lshl_add_u32 v142, v134, 3, v133
	v_lshl_add_u32 v142, v130, 7, v142
	v_lshlrev_b32_e32 v142, 3, v142
	v_and_b32_e32 v143, 15, v102
	v_lshrrev_b32_e32 v144, 1, v143
	v_and_b32_e32 v145, 1, v143
	v_lshrrev_b32_e32 v146, 4, v102
	v_lshlrev_b32_e32 v146, 2, v146
	v_lshl_add_u32 v147, v144, 7, v146
	v_lshlrev_b32_e32 v147, 3, v147
	v_sub_u32_e32 v148, 128, v146
	v_and_b32_e32 v148, 0x7f, v148
	v_lshl_add_u32 v148, v144, 7, v148
	v_lshlrev_b32_e32 v148, 3, v148
	v_sub_u32_e32 v149, 127, v146
	v_and_b32_e32 v149, 0x7f, v149
	v_lshl_add_u32 v149, v144, 7, v149
	v_lshlrev_b32_e32 v149, 3, v149
	v_sub_u32_e32 v150, 126, v146
	v_and_b32_e32 v150, 0x7f, v150
	v_lshl_add_u32 v150, v144, 7, v150
	v_lshlrev_b32_e32 v150, 3, v150
	v_sub_u32_e32 v151, 125, v146
	v_and_b32_e32 v151, 0x7f, v151
	v_lshl_add_u32 v151, v144, 7, v151
	v_lshlrev_b32_e32 v151, 3, v151
	v_cmp_eq_u32_e64 s[26:27], 1, v145
	v_lshrrev_b32_e32 v152, 3, v102
	v_and_b32_e32 v153, 7, v102
	v_lshlrev_b32_e32 v186, 12, v152
	v_lshl_add_u32 v186, v153, 3, v186
	v_lshlrev_b32_e32 v187, 7, v153
	v_add_u32_e32 v187, v187, v152
	v_lshlrev_b32_e32 v187, 3, v187
	v_add_u32_e32 v188, 0x40000, v186
	v_lshlrev_b32_e32 v189, 3, v102
	s_add_i32 s0, s93, 0xffffffa0
	s_add_i32 s1, s74, 0xffffffa0
	s_cmp_eq_u32 s101, 1
	s_cselect_b32 s0, s93, s0
	s_cselect_b32 s1, 0x100, s1
	s_add_u32 s16, s20, 0x380000
	s_addc_u32 s17, s21, 0
	s_load_dwordx2 s[14:15], s[82:83], 0x60
.Lfw_item:
	s_lshl_b32 s25, s0, 4
	s_lshr_b32 s22, s0, 6
	s_and_b32 s25, s25, 0x3f0
	s_lshl_b32 s23, s22, 19
	s_lshl_b32 s24, s25, 2
	s_add_u32 s23, s23, s24
	s_waitcnt lgkmcnt(0)
	s_add_u32 s28, s14, s23
	s_addc_u32 s29, s15, 0
	global_load_dwordx2 v[154:155], v186, s[28:29]
	global_load_dwordx2 v[156:157], v188, s[28:29]
	v_cmp_gt_u32_e32 vcc, 0x80, v102
	s_and_saveexec_b64 s[30:31], vcc
	ds_write_b64 v189, v[184:185] offset:8192
	s_or_b64 exec, exec, s[30:31]
	s_waitcnt vmcnt(0)
	ds_write_b64 v187, v[154:155]
	ds_write_b64 v187, v[156:157] offset:512
	s_waitcnt lgkmcnt(0)
	s_barrier
	v_mov_b32_e32 v170, 0
	v_mov_b32_e32 v171, 0
	v_mov_b32_e32 v172, 0
	v_mov_b32_e32 v173, 0
	v_mov_b32_e32 v180, 0
	v_add_u32_e32 v181, v180, v135
	v_and_b32_e32 v181, 0x380, v181
	v_add_u32_e32 v182, v181, v135
	v_and_b32_e32 v182, 0x380, v182
	v_add_u32_e32 v183, v182, v135
	v_and_b32_e32 v183, 0x380, v183
	ds_read_b64 v[154:155], v137
	ds_read_b64 v[162:163], v180 offset:8192
	ds_read_b64 v[156:157], v137 offset:128
	ds_read_b64 v[164:165], v181 offset:8192
	ds_read_b64 v[158:159], v137 offset:256
	ds_read_b64 v[166:167], v182 offset:8192
	ds_read_b64 v[160:161], v137 offset:384
	ds_read_b64 v[168:169], v183 offset:8192
	s_waitcnt lgkmcnt(0)
	v_fma_f32 v170, v154, v162, v170
	v_fma_f32 v171, v155, v162, v171
	v_fma_f32 v170, v155, v163, v170
	v_fma_f32 v171, -v154, v163, v171
	v_fma_f32 v172, v156, v164, v172
	v_fma_f32 v173, v157, v164, v173
	v_fma_f32 v172, v157, v165, v172
	v_fma_f32 v173, -v156, v165, v173
	v_fma_f32 v170, v158, v166, v170
	v_fma_f32 v171, v159, v166, v171
	v_fma_f32 v170, v159, v167, v170
	v_fma_f32 v171, -v158, v167, v171
	v_fma_f32 v172, v160, v168, v172
	v_fma_f32 v173, v161, v168, v173
	v_fma_f32 v172, v161, v169, v172
	v_fma_f32 v173, -v160, v169, v173
	v_add_u32_e32 v180, v183, v135
	v_and_b32_e32 v180, 0x380, v180
	v_add_u32_e32 v181, v180, v135
	v_and_b32_e32 v181, 0x380, v181
	v_add_u32_e32 v182, v181, v135
	v_and_b32_e32 v182, 0x380, v182
	v_add_u32_e32 v183, v182, v135
	v_and_b32_e32 v183, 0x380, v183
	ds_read_b64 v[154:155], v137 offset:512
	ds_read_b64 v[162:163], v180 offset:8192
	ds_read_b64 v[156:157], v137 offset:640
	ds_read_b64 v[164:165], v181 offset:8192
	ds_read_b64 v[158:159], v137 offset:768
	ds_read_b64 v[166:167], v182 offset:8192
	ds_read_b64 v[160:161], v137 offset:896
	ds_read_b64 v[168:169], v183 offset:8192
	s_waitcnt lgkmcnt(0)
	v_fma_f32 v170, v154, v162, v170
	v_fma_f32 v171, v155, v162, v171
	v_fma_f32 v170, v155, v163, v170
	v_fma_f32 v171, -v154, v163, v171
	v_fma_f32 v172, v156, v164, v172
	v_fma_f32 v173, v157, v164, v173
	v_fma_f32 v172, v157, v165, v172
	v_fma_f32 v173, -v156, v165, v173
	v_fma_f32 v170, v158, v166, v170
	v_fma_f32 v171, v159, v166, v171
	v_fma_f32 v170, v159, v167, v170
	v_fma_f32 v171, -v158, v167, v171
	v_fma_f32 v172, v160, v168, v172
	v_fma_f32 v173, v161, v168, v173
	v_fma_f32 v172, v161, v169, v172
	v_fma_f32 v173, -v160, v169, v173
	v_add_f32_e32 v174, v170, v172
	v_add_f32_e32 v175, v171, v173
	v_sub_f32_e32 v176, v170, v172
	v_sub_f32_e32 v177, v171, v173
	ds_read_b64 v[162:163], v140 offset:8192
	ds_read_b64 v[164:165], v141 offset:8192
	s_waitcnt lgkmcnt(0)
	v_mul_f32_e32 v154, v174, v162
	v_mul_f32_e32 v155, v175, v162
	v_mul_f32_e32 v156, v176, v164
	v_mul_f32_e32 v157, v177, v164
	v_fma_f32 v154, v175, v163, v154
	v_fma_f32 v155, -v174, v163, v155
	v_fma_f32 v156, v177, v165, v156
	v_fma_f32 v157, -v176, v165, v157
	ds_write_b64 v139, v[154:155] offset:12288
	ds_write_b64 v139, v[156:157] offset:12832
	s_waitcnt lgkmcnt(0)
	s_barrier
	v_mov_b32_e32 v170, 0
	v_mov_b32_e32 v171, 0
	v_mov_b32_e32 v172, 0
	v_mov_b32_e32 v173, 0
	v_mov_b32_e32 v180, 0
	v_add_u32_e32 v181, v180, v136
	v_and_b32_e32 v181, 0x3c0, v181
	v_add_u32_e32 v182, v181, v136
	v_and_b32_e32 v182, 0x3c0, v182
	v_add_u32_e32 v183, v182, v136
	v_and_b32_e32 v183, 0x3c0, v183
	ds_read_b64 v[154:155], v138
	ds_read_b64 v[162:163], v180 offset:8192
	ds_read_b64 v[156:157], v138 offset:8
	ds_read_b64 v[164:165], v181 offset:8192
	ds_read_b64 v[158:159], v138 offset:16
	ds_read_b64 v[166:167], v182 offset:8192
	ds_read_b64 v[160:161], v138 offset:24
	ds_read_b64 v[168:169], v183 offset:8192
	s_waitcnt lgkmcnt(0)
	v_fma_f32 v170, v154, v162, v170
	v_fma_f32 v171, v155, v162, v171
	v_fma_f32 v170, v155, v163, v170
	v_fma_f32 v171, -v154, v163, v171
	v_fma_f32 v172, v156, v164, v172
	v_fma_f32 v173, v157, v164, v173
	v_fma_f32 v172, v157, v165, v172
	v_fma_f32 v173, -v156, v165, v173
	v_fma_f32 v170, v158, v166, v170
	v_fma_f32 v171, v159, v166, v171
	v_fma_f32 v170, v159, v167, v170
	v_fma_f32 v171, -v158, v167, v171
	v_fma_f32 v172, v160, v168, v172
	v_fma_f32 v173, v161, v168, v173
	v_fma_f32 v172, v161, v169, v172
	v_fma_f32 v173, -v160, v169, v173
	v_add_u32_e32 v180, v183, v136
	v_and_b32_e32 v180, 0x3c0, v180
	v_add_u32_e32 v181, v180, v136
	v_and_b32_e32 v181, 0x3c0, v181
	v_add_u32_e32 v182, v181, v136
	v_and_b32_e32 v182, 0x3c0, v182
	v_add_u32_e32 v183, v182, v136
	v_and_b32_e32 v183, 0x3c0, v183
	ds_read_b64 v[154:155], v138 offset:32
	ds_read_b64 v[162:163], v180 offset:8192
	ds_read_b64 v[156:157], v138 offset:40
	ds_read_b64 v[164:165], v181 offset:8192
	ds_read_b64 v[158:159], v138 offset:48
	ds_read_b64 v[166:167], v182 offset:8192
	ds_read_b64 v[160:161], v138 offset:56
	ds_read_b64 v[168:169], v183 offset:8192
	s_waitcnt lgkmcnt(0)
	v_fma_f32 v170, v154, v162, v170
	v_fma_f32 v171, v155, v162, v171
	v_fma_f32 v170, v155, v163, v170
	v_fma_f32 v171, -v154, v163, v171
	v_fma_f32 v172, v156, v164, v172
	v_fma_f32 v173, v157, v164, v173
	v_fma_f32 v172, v157, v165, v172
	v_fma_f32 v173, -v156, v165, v173
	v_fma_f32 v170, v158, v166, v170
	v_fma_f32 v171, v159, v166, v171
	v_fma_f32 v170, v159, v167, v170
	v_fma_f32 v171, -v158, v167, v171
	v_fma_f32 v172, v160, v168, v172
	v_fma_f32 v173, v161, v168, v173
	v_fma_f32 v172, v161, v169, v172
	v_fma_f32 v173, -v160, v169, v173
	v_add_u32_e32 v180, v183, v136
	v_and_b32_e32 v180, 0x3c0, v180
	v_add_u32_e32 v181, v180, v136
	v_and_b32_e32 v181, 0x3c0, v181
	v_add_u32_e32 v182, v181, v136
	v_and_b32_e32 v182, 0x3c0, v182
	v_add_u32_e32 v183, v182, v136
	v_and_b32_e32 v183, 0x3c0, v183
	ds_read_b64 v[154:155], v138 offset:64
	ds_read_b64 v[162:163], v180 offset:8192
	ds_read_b64 v[156:157], v138 offset:72
	ds_read_b64 v[164:165], v181 offset:8192
	ds_read_b64 v[158:159], v138 offset:80
	ds_read_b64 v[166:167], v182 offset:8192
	ds_read_b64 v[160:161], v138 offset:88
	ds_read_b64 v[168:169], v183 offset:8192
	s_waitcnt lgkmcnt(0)
	v_fma_f32 v170, v154, v162, v170
	v_fma_f32 v171, v155, v162, v171
	v_fma_f32 v170, v155, v163, v170
	v_fma_f32 v171, -v154, v163, v171
	v_fma_f32 v172, v156, v164, v172
	v_fma_f32 v173, v157, v164, v173
	v_fma_f32 v172, v157, v165, v172
	v_fma_f32 v173, -v156, v165, v173
	v_fma_f32 v170, v158, v166, v170
	v_fma_f32 v171, v159, v166, v171
	v_fma_f32 v170, v159, v167, v170
	v_fma_f32 v171, -v158, v167, v171
	v_fma_f32 v172, v160, v168, v172
	v_fma_f32 v173, v161, v168, v173
	v_fma_f32 v172, v161, v169, v172
	v_fma_f32 v173, -v160, v169, v173
	v_add_u32_e32 v180, v183, v136
	v_and_b32_e32 v180, 0x3c0, v180
	v_add_u32_e32 v181, v180, v136
	v_and_b32_e32 v181, 0x3c0, v181
	v_add_u32_e32 v182, v181, v136
	v_and_b32_e32 v182, 0x3c0, v182
	v_add_u32_e32 v183, v182, v136
	v_and_b32_e32 v183, 0x3c0, v183
	ds_read_b64 v[154:155], v138 offset:96
	ds_read_b64 v[162:163], v180 offset:8192
	ds_read_b64 v[156:157], v138 offset:104
	ds_read_b64 v[164:165], v181 offset:8192
	ds_read_b64 v[158:159], v138 offset:112
	ds_read_b64 v[166:167], v182 offset:8192
	ds_read_b64 v[160:161], v138 offset:120
	ds_read_b64 v[168:169], v183 offset:8192
	s_waitcnt lgkmcnt(0)
	v_fma_f32 v170, v154, v162, v170
	v_fma_f32 v171, v155, v162, v171
	v_fma_f32 v170, v155, v163, v170
	v_fma_f32 v171, -v154, v163, v171
	v_fma_f32 v172, v156, v164, v172
	v_fma_f32 v173, v157, v164, v173
	v_fma_f32 v172, v157, v165, v172
	v_fma_f32 v173, -v156, v165, v173
	v_fma_f32 v170, v158, v166, v170
	v_fma_f32 v171, v159, v166, v171
	v_fma_f32 v170, v159, v167, v170
	v_fma_f32 v171, -v158, v167, v171
	v_fma_f32 v172, v160, v168, v172
	v_fma_f32 v173, v161, v168, v173
	v_fma_f32 v172, v161, v169, v172
	v_fma_f32 v173, -v160, v169, v173
	v_add_f32_e32 v174, v170, v172
	v_add_f32_e32 v175, v171, v173
	v_sub_f32_e32 v176, v170, v172
	v_sub_f32_e32 v177, v171, v173
	ds_write_b64 v142, v[174:175] offset:24576
	ds_write_b64 v142, v[176:177] offset:25088
	s_waitcnt lgkmcnt(0)
	s_barrier
	ds_read_b128 v[154:157], v147 offset:24576
	ds_read_b128 v[158:161], v147 offset:24592
	ds_read_b64 v[162:163], v148 offset:24576
	ds_read_b64 v[164:165], v149 offset:24576
	ds_read_b64 v[166:167], v150 offset:24576
	ds_read_b64 v[168:169], v151 offset:24576
	v_add_u32_e32 v190, s25, v143
	v_mul_u32_u24_e32 v190, 0xc00, v190
	v_lshl_add_u32 v190, v146, 1, v190
	s_lshl_b32 s24, s22, 8
	v_add_u32_e32 v190, s24, v190
	s_waitcnt lgkmcnt(0)
	v_cndmask_b32_e64 v191, v154, v155, s[26:27]
	v_cndmask_b32_e64 v192, v162, v163, s[26:27]
	v_cndmask_b32_e64 v193, v163, v154, s[26:27]
	v_cndmask_b32_e64 v194, v155, v162, s[26:27]
	v_add_f32_e32 v170, v191, v192
	v_sub_f32_e32 v174, v193, v194
	v_cndmask_b32_e64 v191, v156, v157, s[26:27]
	v_cndmask_b32_e64 v192, v164, v165, s[26:27]
	v_cndmask_b32_e64 v193, v165, v156, s[26:27]
	v_cndmask_b32_e64 v194, v157, v164, s[26:27]
	v_add_f32_e32 v171, v191, v192
	v_sub_f32_e32 v175, v193, v194
	v_cndmask_b32_e64 v191, v158, v159, s[26:27]
	v_cndmask_b32_e64 v192, v166, v167, s[26:27]
	v_cndmask_b32_e64 v193, v167, v158, s[26:27]
	v_cndmask_b32_e64 v194, v159, v166, s[26:27]
	v_add_f32_e32 v172, v191, v192
	v_sub_f32_e32 v176, v193, v194
	v_cndmask_b32_e64 v191, v160, v161, s[26:27]
	v_cndmask_b32_e64 v192, v168, v169, s[26:27]
	v_cndmask_b32_e64 v193, v169, v160, s[26:27]
	v_cndmask_b32_e64 v194, v161, v168, s[26:27]
	v_add_f32_e32 v173, v191, v192
	v_sub_f32_e32 v177, v193, v194
	v_mul_f32_e32 v170, 0x3d3504f3, v170
	v_mul_f32_e32 v171, 0x3d3504f3, v171
	v_mul_f32_e32 v172, 0x3d3504f3, v172
	v_mul_f32_e32 v173, 0x3d3504f3, v173
	v_mul_f32_e32 v174, 0x3d3504f3, v174
	v_mul_f32_e32 v175, 0x3d3504f3, v175
	v_mul_f32_e32 v176, 0x3d3504f3, v176
	v_mul_f32_e32 v177, 0x3d3504f3, v177
	s_nop 0
	v_cvt_pk_bf16_f32 v178, v170, v171
	v_cvt_pk_bf16_f32 v179, v172, v173
	v_cvt_pk_bf16_f32 v180, v174, v175
	v_cvt_pk_bf16_f32 v181, v176, v177
	global_store_dwordx2 v190, v[178:179], s[16:17]
	global_store_dwordx2 v190, v[180:181], s[16:17] offset:1024
	s_add_i32 s0, s1, s0
	s_cmpk_lt_i32 s0, 0x100
	s_barrier
	s_cbranch_scc1 .Lfw_item
	s_cmp_eq_u32 s98, 1
	s_cbranch_scc0 .Lfw_after
	s_mov_b32 s98, 2
	s_branch .Lad_body
.Lfw_after:
.LBB0_71:
	s_add_i32 s0, s74, -1
	s_cmp_lg_u32 s93, s0
	s_cbranch_scc1 .LBB0_76
	s_movk_i32 s0, 0x400
	v_cmp_gt_i32_e32 vcc, s0, v102
	s_and_saveexec_b64 s[4:5], vcc
	s_cbranch_execz .LBB0_75
	v_and_b32_e32 v2, 15, v105
	v_cvt_f32_ubyte0_e32 v2, v2
	v_mul_f32_e32 v2, 0xbf549a78, v2
	v_exp_f32_e32 v4, v2
	s_add_u32 s6, s20, 0x50000
	v_lshlrev_b32_e32 v2, 1, v105
	s_addc_u32 s7, s21, 0
	v_lshl_add_u32 v2, s64, 7, v2
	s_mov_b64 s[8:9], 0
	s_movk_i32 s0, 0x1ff

.LBB0_76:
	s_cmpk_eq_i32 s74, 0x100
	s_mov_b32 s2, 0
	s_cselect_b64 s[10:11], -1, 0
	s_barrier
	s_load_dwordx2 s[4:5], s[82:83], 0xb0
	s_and_b64 s[0:1], s[10:11], exec
	s_cselect_b32 s65, 0x60, 0
	s_cmp_ge_i32 s93, s65
	s_cselect_b64 s[0:1], -1, 0
	s_mov_b32 s97, s65
	s_cmp_eq_u32 s101, 1
	s_cselect_b32 s97, 0xc0, s97
	s_cmp_lt_i32 s93, s97
	v_writelane_b32 v254, s0, 0
	s_nop 1
	v_writelane_b32 v254, s1, 1
	s_cbranch_scc1 .LBB0_85
	s_sub_i32 s0, s93, s97
	s_cmpk_gt_i32 s0, 0x6f
	s_cbranch_scc1 .LBB0_85
	s_load_dwordx2 s[6:7], s[82:83], 0x58
	s_load_dwordx2 s[8:9], s[82:83], 0x60
	s_load_dwordx2 s[12:13], s[82:83], 0x40
	s_waitcnt lgkmcnt(0)
	s_load_dwordx2 s[12:13], s[82:83], 0x48
	s_sub_i32 s1, s74, s97
	s_waitcnt lgkmcnt(0)
	s_add_i32 s12, s0, 0xb0
	v_mbcnt_lo_u32_b32 v2, -1, s2
	s_add_u32 s2, s8, 0x200000
	s_addc_u32 s8, s9, 0
	s_cmpk_lt_i32 s0, 0x50
	s_cselect_b32 s6, s6, s2
	s_movk_i32 s2, 0x500
	s_cselect_b32 s14, s2, 0x400
	s_cselect_b32 s7, s7, s8
	s_cselect_b32 s12, s0, s12
	s_lshr_b32 s13, s14, 7
	s_sext_i32_i8 s15, s13
	v_mbcnt_hi_u32_b32 v37, -1, v2
	v_cvt_f32_i32_e32 v2, s15
	s_load_dwordx2 s[8:9], s[82:83], 0x50
	s_waitcnt lgkmcnt(0)
	s_sext_i32_i8 s8, s12
	v_cvt_f32_i32_e32 v3, s8
	v_rcp_iflag_f32_e32 v4, v2
	s_xor_b32 s8, s8, s15
	s_ashr_i32 s8, s8, 30
	s_or_b32 s15, s8, 1
	v_mul_f32_e32 v4, v3, v4
	v_trunc_f32_e32 v4, v4
	v_fma_f32 v3, -v4, v2, v3
	v_cvt_i32_f32_e32 v4, v4
	v_cmp_ge_f32_e64 s[8:9], |v3|, |v2|
	s_and_b64 s[8:9], s[8:9], exec
	s_cselect_b32 s8, s15, 0
	v_readfirstlane_b32 s9, v4
	s_add_i32 s8, s9, s8
	s_sext_i32_i8 s9, s8
	s_mul_i32 s8, s8, s13
	v_add_u32_e32 v41, s72, v37
	s_sub_i32 s8, s12, s8
	s_sext_i32_i8 s8, s8
	v_ashrrev_i32_e32 v40, 5, v41
	s_lshl_b32 s8, s8, 7
	v_lshl_add_u32 v30, s9, 7, v40
	v_lshlrev_b32_e32 v2, 2, v37
	s_ashr_i32 s9, s8, 31
	v_and_b32_e32 v36, 0x7c, v2
	v_mad_i64_i32 v[2:3], s[12:13], v30, s14, 0
	v_lshl_add_u64 v[2:3], v[2:3], 2, s[6:7]
	s_lshl_b64 s[8:9], s[8:9], 2
	v_mov_b32_e32 v35, 0
	v_lshl_add_u64 v[2:3], v[2:3], 0, s[8:9]
	v_lshlrev_b32_e32 v34, 2, v36
	v_lshl_add_u64 v[10:11], v[2:3], 0, v[34:35]
	v_add_u32_e32 v2, 16, v30
	v_mad_i64_i32 v[2:3], s[12:13], v2, s14, 0
	v_lshl_add_u64 v[2:3], v[2:3], 2, s[6:7]
	v_lshl_add_u64 v[2:3], v[2:3], 0, s[8:9]
	v_lshl_add_u64 v[12:13], v[2:3], 0, v[34:35]
	global_load_dwordx4 v[2:5], v[10:11], off
	global_load_dwordx4 v[6:9], v[12:13], off
	v_add_u32_e32 v10, 32, v30
	v_mad_i64_i32 v[10:11], s[12:13], v10, s14, 0
	v_lshl_add_u64 v[10:11], v[10:11], 2, s[6:7]
	v_lshl_add_u64 v[10:11], v[10:11], 0, s[8:9]
	v_lshl_add_u64 v[18:19], v[10:11], 0, v[34:35]
	v_add_u32_e32 v10, 48, v30
	v_mad_i64_i32 v[10:11], s[12:13], v10, s14, 0
	v_lshl_add_u64 v[10:11], v[10:11], 2, s[6:7]
	v_lshl_add_u64 v[10:11], v[10:11], 0, s[8:9]
	v_lshl_add_u64 v[20:21], v[10:11], 0, v[34:35]
	global_load_dwordx4 v[10:13], v[18:19], off
	global_load_dwordx4 v[14:17], v[20:21], off
	v_add_u32_e32 v18, 64, v30
	v_mad_i64_i32 v[18:19], s[12:13], v18, s14, 0
	v_lshl_add_u64 v[18:19], v[18:19], 2, s[6:7]
	v_lshl_add_u64 v[18:19], v[18:19], 0, s[8:9]
	v_lshl_add_u64 v[26:27], v[18:19], 0, v[34:35]
	v_add_u32_e32 v18, 0x50, v30
	v_mad_i64_i32 v[18:19], s[12:13], v18, s14, 0
	v_lshl_add_u64 v[18:19], v[18:19], 2, s[6:7]
	v_lshl_add_u64 v[18:19], v[18:19], 0, s[8:9]
	v_lshl_add_u64 v[28:29], v[18:19], 0, v[34:35]
	global_load_dwordx4 v[18:21], v[26:27], off
	global_load_dwordx4 v[22:25], v[28:29], off
	v_add_u32_e32 v26, 0x60, v30
	v_mad_i64_i32 v[26:27], s[12:13], v26, s14, 0
	v_lshl_add_u64 v[26:27], v[26:27], 2, s[6:7]
	v_lshl_add_u64 v[26:27], v[26:27], 0, s[8:9]
	v_lshl_add_u64 v[38:39], v[26:27], 0, v[34:35]
	v_add_u32_e32 v26, 0x70, v30
	v_mad_i64_i32 v[26:27], s[12:13], v26, s14, 0
	v_lshl_add_u64 v[26:27], v[26:27], 2, s[6:7]
	v_lshl_add_u64 v[26:27], v[26:27], 0, s[8:9]
	v_lshl_add_u64 v[42:43], v[26:27], 0, v[34:35]
	global_load_dwordx4 v[26:29], v[38:39], off
	global_load_dwordx4 v[30:33], v[42:43], off
	v_and_b32_e32 v37, 7, v37
	v_ashrrev_i32_e32 v41, 3, v41
	v_add_u32_e32 v39, 0, v34
	s_movk_i32 s6, 0x204
	v_lshlrev_b32_e32 v34, 3, v37
	v_mul_u32_u24_e32 v37, 0x1020, v37
	v_lshlrev_b32_e32 v38, 2, v41
	v_mul_lo_u32 v44, v40, s6
	v_add3_u32 v42, 0, v37, v38
	v_or_b32_e32 v38, 64, v34
	s_lshl_b32 s6, s97, 1
	s_mov_b32 s7, 0
	v_add_u32_e32 v43, 0x8100, v42
	s_sub_i32 s20, 0, s97
	s_sub_i32 s21, s74, s6
	v_add_u32_e32 v44, v39, v44
	v_lshlrev_b32_e32 v36, 2, v36
	v_lshlrev_b32_e32 v34, 1, v34
	v_lshlrev_b32_e32 v38, 1, v38
	s_mov_b32 s22, s93
	s_branch .LBB0_80
